# K-loop MFMA order variant: accumulate-chain pairs in row-major serpentine (A operand shared across four pairs), alternating k-step order
# speedup vs baseline: 1.0223x; 1.0010x over previous
.LBB0_159:
	s_ashr_i32 s29, s28, 31
	s_lshl_b64 s[24:25], s[28:29], 19
	s_add_u32 s24, s34, s24
	s_addc_u32 s25, s35, s25
	s_and_b64 s[30:31], s[18:19], exec
	s_cselect_b32 s29, s25, s41
	s_cselect_b32 s43, s24, s40
	s_ashr_i32 s21, s20, 31
	s_lshl_b64 s[30:31], s[20:21], 19
	s_add_u32 s30, s36, s30
	s_addc_u32 s31, s37, s31
	s_and_b64 s[56:57], s[18:19], exec
	s_cselect_b32 s21, s31, s27
	s_cselect_b32 s55, s30, s26
	s_add_u32 s40, s40, 0x40080
	s_addc_u32 s41, s41, 0
	s_add_u32 s56, s26, 0x100
	s_addc_u32 s57, s27, 0
	s_mov_b32 s58, -2
	s_add_u32 s26, s40, 0xfffc0080
	s_addc_u32 s27, s41, -1
	s_add_i32 s59, 0, 0x10000
	s_cmp_eq_u32 s58, 12
	s_cselect_b32 vcc_hi, s29, s27
	s_cselect_b32 vcc_lo, s43, s26
	v_add_u32_e32 v0, s59, v167
	s_cselect_b32 s27, s21, s57
	s_cselect_b32 s26, s55, s56
	s_add_i32 s62, 0, 0x14000
	ds_read_b128 v[142:145], v0
	ds_read_b128 v[146:149], v0 offset:1024
	ds_read_b128 v[150:153], v0 offset:2048
	ds_read_b128 v[154:157], v0 offset:3072
	v_add_u32_e32 v0, s62, v167
	ds_read_b128 v[158:161], v0
	ds_read_b128 v[162:165], v0 offset:1024
	ds_read_b128 v[174:177], v0 offset:2048
	ds_read_b128 v[178:181], v0 offset:3072
	v_lshl_add_u64 v[214:215], s[40:41], 0, v[138:139]
	s_add_i32 m0, s23, 0xc000
	ds_read_b128 v[182:185], v173
	ds_read_b128 v[186:189], v173 offset:1024
	ds_read_b128 v[190:193], v173 offset:2048
	ds_read_b128 v[194:197], v173 offset:3072
	ds_read_b128 v[198:201], v173 offset:4096
	ds_read_b128 v[202:205], v173 offset:5120
	ds_read_b128 v[206:209], v173 offset:6144
	ds_read_b128 v[210:213], v173 offset:7168
	global_load_lds_dwordx4 v[214:215], off
	v_lshl_add_u64 v[214:215], s[40:41], 0, v[140:141]
	s_add_i32 m0, s23, 0xe000
	s_nop 0
	global_load_lds_dwordx4 v[214:215], off
	s_waitcnt vmcnt(8)
	s_waitcnt lgkmcnt(0)
	s_barrier
	s_waitcnt lgkmcnt(0)
	v_mfma_f32_16x16x32_bf16 v[126:129], v[142:145], v[182:185], 0
	v_mfma_f32_16x16x32_bf16 v[126:129], v[146:149], v[186:189], v[126:129]
	v_mfma_f32_16x16x32_bf16 v[118:121], v[146:149], v[194:197], 0
	v_mfma_f32_16x16x32_bf16 v[118:121], v[142:145], v[190:193], v[118:121]
	v_mfma_f32_16x16x32_bf16 v[110:113], v[142:145], v[198:201], 0
	v_mfma_f32_16x16x32_bf16 v[110:113], v[146:149], v[202:205], v[110:113]
	v_mfma_f32_16x16x32_bf16 v[102:105], v[146:149], v[210:213], 0
	v_mfma_f32_16x16x32_bf16 v[102:105], v[142:145], v[206:209], v[102:105]
	v_mfma_f32_16x16x32_bf16 v[98:101], v[150:153], v[206:209], 0
	v_mfma_f32_16x16x32_bf16 v[98:101], v[154:157], v[210:213], v[98:101]
	v_mfma_f32_16x16x32_bf16 v[106:109], v[154:157], v[202:205], 0
	v_mfma_f32_16x16x32_bf16 v[106:109], v[150:153], v[198:201], v[106:109]
	v_mfma_f32_16x16x32_bf16 v[114:117], v[150:153], v[190:193], 0
	v_mfma_f32_16x16x32_bf16 v[114:117], v[154:157], v[194:197], v[114:117]
	v_mfma_f32_16x16x32_bf16 v[122:125], v[154:157], v[186:189], 0
	v_mfma_f32_16x16x32_bf16 v[122:125], v[150:153], v[182:185], v[122:125]
	v_mfma_f32_16x16x32_bf16 v[82:85], v[158:161], v[182:185], 0
	v_mfma_f32_16x16x32_bf16 v[82:85], v[162:165], v[186:189], v[82:85]
	v_mfma_f32_16x16x32_bf16 v[70:73], v[162:165], v[194:197], 0
	v_mfma_f32_16x16x32_bf16 v[70:73], v[158:161], v[190:193], v[70:73]
	v_mfma_f32_16x16x32_bf16 v[54:57], v[158:161], v[198:201], 0
	v_mfma_f32_16x16x32_bf16 v[54:57], v[162:165], v[202:205], v[54:57]
	v_mfma_f32_16x16x32_bf16 v[38:41], v[162:165], v[210:213], 0
	v_mfma_f32_16x16x32_bf16 v[38:41], v[158:161], v[206:209], v[38:41]
	v_mfma_f32_16x16x32_bf16 v[34:37], v[174:177], v[206:209], 0
	v_mfma_f32_16x16x32_bf16 v[34:37], v[178:181], v[210:213], v[34:37]
	v_mfma_f32_16x16x32_bf16 v[46:49], v[178:181], v[202:205], 0
	v_mfma_f32_16x16x32_bf16 v[46:49], v[174:177], v[198:201], v[46:49]
	v_mfma_f32_16x16x32_bf16 v[62:65], v[174:177], v[190:193], 0
	v_mfma_f32_16x16x32_bf16 v[62:65], v[178:181], v[194:197], v[62:65]
	v_mfma_f32_16x16x32_bf16 v[74:77], v[178:181], v[186:189], 0
	v_mfma_f32_16x16x32_bf16 v[74:77], v[174:177], v[182:185], v[74:77]
	s_barrier
	s_add_i32 s59, s59, s44
	v_lshl_add_u64 v[214:215], s[26:27], 0, v[132:133]
	s_mov_b32 m0, s59
	ds_read_b128 v[182:185], v173 offset:16384
	ds_read_b128 v[186:189], v173 offset:17408
	ds_read_b128 v[190:193], v173 offset:18432
	ds_read_b128 v[194:197], v173 offset:19456
	ds_read_b128 v[198:201], v173 offset:20480
	ds_read_b128 v[202:205], v173 offset:21504
	ds_read_b128 v[206:209], v173 offset:22528
	ds_read_b128 v[210:213], v173 offset:23552
	global_load_lds_dwordx4 v[214:215], off
	s_add_i32 m0, s59, 0x2000
	s_add_u32 s60, s26, 0x40000
	v_lshl_add_u64 v[216:217], s[26:27], 0, v[136:137]
	s_addc_u32 s61, s27, 0
	s_add_i32 s59, s62, s44
	global_load_lds_dwordx4 v[216:217], off
	v_lshl_add_u64 v[218:219], s[60:61], 0, v[132:133]
	s_mov_b32 m0, s59
	v_lshl_add_u64 v[220:221], vcc, 0, v[134:135]
	global_load_lds_dwordx4 v[218:219], off
	v_lshl_add_u64 v[218:219], s[60:61], 0, v[136:137]
	s_add_i32 m0, s59, 0x2000
	s_nop 0
	global_load_lds_dwordx4 v[218:219], off
	v_lshl_add_u64 v[218:219], vcc, 0, v[130:131]
	s_mov_b32 m0, s23
	s_nop 0
	global_load_lds_dwordx4 v[218:219], off
	s_mov_b32 m0, s45
	s_nop 0
	global_load_lds_dwordx4 v[220:221], off
	s_waitcnt vmcnt(8)
	s_waitcnt lgkmcnt(0)
	s_barrier
	s_waitcnt lgkmcnt(0)
	v_mfma_f32_16x16x32_bf16 v[94:97], v[142:145], v[182:185], 0
	v_mfma_f32_16x16x32_bf16 v[94:97], v[146:149], v[186:189], v[94:97]
	v_mfma_f32_16x16x32_bf16 v[86:89], v[146:149], v[194:197], 0
	v_mfma_f32_16x16x32_bf16 v[86:89], v[142:145], v[190:193], v[86:89]
	v_mfma_f32_16x16x32_bf16 v[66:69], v[142:145], v[198:201], 0
	v_mfma_f32_16x16x32_bf16 v[66:69], v[146:149], v[202:205], v[66:69]
	v_mfma_f32_16x16x32_bf16 v[50:53], v[146:149], v[210:213], 0
	v_mfma_f32_16x16x32_bf16 v[50:53], v[142:145], v[206:209], v[50:53]
	v_mfma_f32_16x16x32_bf16 v[42:45], v[150:153], v[206:209], 0
	v_mfma_f32_16x16x32_bf16 v[42:45], v[154:157], v[210:213], v[42:45]
	v_mfma_f32_16x16x32_bf16 v[58:61], v[154:157], v[202:205], 0
	v_mfma_f32_16x16x32_bf16 v[58:61], v[150:153], v[198:201], v[58:61]
	v_mfma_f32_16x16x32_bf16 v[78:81], v[150:153], v[190:193], 0
	v_mfma_f32_16x16x32_bf16 v[78:81], v[154:157], v[194:197], v[78:81]
	v_mfma_f32_16x16x32_bf16 v[90:93], v[154:157], v[186:189], 0
	v_mfma_f32_16x16x32_bf16 v[90:93], v[150:153], v[182:185], v[90:93]
	v_mfma_f32_16x16x32_bf16 v[30:33], v[158:161], v[182:185], 0
	v_mfma_f32_16x16x32_bf16 v[30:33], v[162:165], v[186:189], v[30:33]
	v_mfma_f32_16x16x32_bf16 v[22:25], v[162:165], v[194:197], 0
	v_mfma_f32_16x16x32_bf16 v[22:25], v[158:161], v[190:193], v[22:25]
	v_mfma_f32_16x16x32_bf16 v[14:17], v[158:161], v[198:201], 0
	v_mfma_f32_16x16x32_bf16 v[14:17], v[162:165], v[202:205], v[14:17]
	v_mfma_f32_16x16x32_bf16 v[6:9], v[162:165], v[210:213], 0
	v_mfma_f32_16x16x32_bf16 v[6:9], v[158:161], v[206:209], v[6:9]
	v_mfma_f32_16x16x32_bf16 v[2:5], v[174:177], v[206:209], 0
	v_mfma_f32_16x16x32_bf16 v[2:5], v[178:181], v[210:213], v[2:5]
	v_mfma_f32_16x16x32_bf16 v[10:13], v[178:181], v[202:205], 0
	v_mfma_f32_16x16x32_bf16 v[10:13], v[174:177], v[198:201], v[10:13]
	v_mfma_f32_16x16x32_bf16 v[18:21], v[174:177], v[190:193], 0
	v_mfma_f32_16x16x32_bf16 v[18:21], v[178:181], v[194:197], v[18:21]
	v_mfma_f32_16x16x32_bf16 v[26:29], v[178:181], v[186:189], 0
	v_mfma_f32_16x16x32_bf16 v[26:29], v[174:177], v[182:185], v[26:29]
	s_barrier
	s_add_i32 s59, 0, 0x18000
	v_add_u32_e32 v0, s59, v167
	s_add_i32 s62, 0, 0x1c000
	ds_read_b128 v[142:145], v0
	ds_read_b128 v[146:149], v0 offset:1024
	ds_read_b128 v[150:153], v0 offset:2048
	ds_read_b128 v[154:157], v0 offset:3072
	v_add_u32_e32 v0, s62, v167
	ds_read_b128 v[158:161], v0
	ds_read_b128 v[162:165], v0 offset:1024
	ds_read_b128 v[174:177], v0 offset:2048
	ds_read_b128 v[178:181], v0 offset:3072
	s_add_u32 s60, vcc_lo, 0x40000
	s_addc_u32 s61, vcc_hi, 0
	s_mov_b32 m0, s47
	v_lshl_add_u64 v[222:223], s[60:61], 0, v[130:131]
	ds_read_b128 v[182:185], v173 offset:32768
	ds_read_b128 v[186:189], v173 offset:33792
	ds_read_b128 v[190:193], v173 offset:34816
	ds_read_b128 v[194:197], v173 offset:35840
	ds_read_b128 v[198:201], v173 offset:36864
	ds_read_b128 v[202:205], v173 offset:37888
	ds_read_b128 v[206:209], v173 offset:38912
	ds_read_b128 v[210:213], v173 offset:39936
	global_load_lds_dwordx4 v[222:223], off
	v_lshl_add_u64 v[222:223], s[60:61], 0, v[134:135]
	s_mov_b32 m0, s49
	s_nop 0
	global_load_lds_dwordx4 v[222:223], off
	s_waitcnt vmcnt(8)
	s_waitcnt lgkmcnt(0)
	s_barrier
	s_waitcnt lgkmcnt(0)
	v_mfma_f32_16x16x32_bf16 v[126:129], v[142:145], v[182:185], v[126:129]
	v_mfma_f32_16x16x32_bf16 v[126:129], v[146:149], v[186:189], v[126:129]
	v_mfma_f32_16x16x32_bf16 v[118:121], v[146:149], v[194:197], v[118:121]
	v_mfma_f32_16x16x32_bf16 v[118:121], v[142:145], v[190:193], v[118:121]
	v_mfma_f32_16x16x32_bf16 v[110:113], v[142:145], v[198:201], v[110:113]
	v_mfma_f32_16x16x32_bf16 v[110:113], v[146:149], v[202:205], v[110:113]
	v_mfma_f32_16x16x32_bf16 v[102:105], v[146:149], v[210:213], v[102:105]
	v_mfma_f32_16x16x32_bf16 v[102:105], v[142:145], v[206:209], v[102:105]
	v_mfma_f32_16x16x32_bf16 v[98:101], v[150:153], v[206:209], v[98:101]
	v_mfma_f32_16x16x32_bf16 v[98:101], v[154:157], v[210:213], v[98:101]
	v_mfma_f32_16x16x32_bf16 v[106:109], v[154:157], v[202:205], v[106:109]
	v_mfma_f32_16x16x32_bf16 v[106:109], v[150:153], v[198:201], v[106:109]
	v_mfma_f32_16x16x32_bf16 v[114:117], v[150:153], v[190:193], v[114:117]
	v_mfma_f32_16x16x32_bf16 v[114:117], v[154:157], v[194:197], v[114:117]
	v_mfma_f32_16x16x32_bf16 v[122:125], v[154:157], v[186:189], v[122:125]
	v_mfma_f32_16x16x32_bf16 v[122:125], v[150:153], v[182:185], v[122:125]
	v_mfma_f32_16x16x32_bf16 v[82:85], v[158:161], v[182:185], v[82:85]
	v_mfma_f32_16x16x32_bf16 v[82:85], v[162:165], v[186:189], v[82:85]
	v_mfma_f32_16x16x32_bf16 v[70:73], v[162:165], v[194:197], v[70:73]
	v_mfma_f32_16x16x32_bf16 v[70:73], v[158:161], v[190:193], v[70:73]
	v_mfma_f32_16x16x32_bf16 v[54:57], v[158:161], v[198:201], v[54:57]
	v_mfma_f32_16x16x32_bf16 v[54:57], v[162:165], v[202:205], v[54:57]
	v_mfma_f32_16x16x32_bf16 v[38:41], v[162:165], v[210:213], v[38:41]
	v_mfma_f32_16x16x32_bf16 v[38:41], v[158:161], v[206:209], v[38:41]
	v_mfma_f32_16x16x32_bf16 v[34:37], v[174:177], v[206:209], v[34:37]
	v_mfma_f32_16x16x32_bf16 v[34:37], v[178:181], v[210:213], v[34:37]
	v_mfma_f32_16x16x32_bf16 v[46:49], v[178:181], v[202:205], v[46:49]
	v_mfma_f32_16x16x32_bf16 v[46:49], v[174:177], v[198:201], v[46:49]
	v_mfma_f32_16x16x32_bf16 v[62:65], v[174:177], v[190:193], v[62:65]
	v_mfma_f32_16x16x32_bf16 v[62:65], v[178:181], v[194:197], v[62:65]
	v_mfma_f32_16x16x32_bf16 v[74:77], v[178:181], v[186:189], v[74:77]
	v_mfma_f32_16x16x32_bf16 v[74:77], v[174:177], v[182:185], v[74:77]
	s_barrier
	s_add_i32 s59, s59, s44
	v_lshl_add_u64 v[214:215], v[214:215], 0, s[98:99]
	s_mov_b32 m0, s59
	ds_read_b128 v[182:185], v173 offset:49152
	ds_read_b128 v[186:189], v173 offset:50176
	ds_read_b128 v[190:193], v173 offset:51200
	ds_read_b128 v[194:197], v173 offset:52224
	ds_read_b128 v[198:201], v173 offset:53248
	ds_read_b128 v[202:205], v173 offset:54272
	ds_read_b128 v[206:209], v173 offset:55296
	ds_read_b128 v[210:213], v173 offset:56320
	global_load_lds_dwordx4 v[214:215], off
	s_add_i32 m0, s59, 0x2000
	s_add_u32 s26, s26, 0x40080
	v_lshl_add_u64 v[214:215], v[216:217], 0, s[98:99]
	s_addc_u32 s27, s27, 0
	s_add_i32 s59, s62, s44
	global_load_lds_dwordx4 v[214:215], off
	v_lshl_add_u64 v[214:215], s[26:27], 0, v[132:133]
	s_mov_b32 m0, s59
	s_nop 0
	global_load_lds_dwordx4 v[214:215], off
	v_lshl_add_u64 v[214:215], s[26:27], 0, v[136:137]
	s_add_i32 m0, s59, 0x2000
	s_nop 0
	global_load_lds_dwordx4 v[214:215], off
	v_lshl_add_u64 v[214:215], v[218:219], 0, s[98:99]
	s_mov_b32 m0, s52
	s_nop 0
	global_load_lds_dwordx4 v[214:215], off
	v_lshl_add_u64 v[214:215], v[220:221], 0, s[98:99]
	s_mov_b32 m0, s53
	s_nop 0
	global_load_lds_dwordx4 v[214:215], off
	s_waitcnt vmcnt(8)
	s_waitcnt lgkmcnt(0)
	s_barrier
	s_waitcnt lgkmcnt(0)
	v_mfma_f32_16x16x32_bf16 v[94:97], v[142:145], v[182:185], v[94:97]
	v_mfma_f32_16x16x32_bf16 v[94:97], v[146:149], v[186:189], v[94:97]
	v_mfma_f32_16x16x32_bf16 v[86:89], v[146:149], v[194:197], v[86:89]
	v_mfma_f32_16x16x32_bf16 v[86:89], v[142:145], v[190:193], v[86:89]
	v_mfma_f32_16x16x32_bf16 v[66:69], v[142:145], v[198:201], v[66:69]
	v_mfma_f32_16x16x32_bf16 v[66:69], v[146:149], v[202:205], v[66:69]
	v_mfma_f32_16x16x32_bf16 v[50:53], v[146:149], v[210:213], v[50:53]
	v_mfma_f32_16x16x32_bf16 v[50:53], v[142:145], v[206:209], v[50:53]
	v_mfma_f32_16x16x32_bf16 v[42:45], v[150:153], v[206:209], v[42:45]
	v_mfma_f32_16x16x32_bf16 v[42:45], v[154:157], v[210:213], v[42:45]
	v_mfma_f32_16x16x32_bf16 v[58:61], v[154:157], v[202:205], v[58:61]
	v_mfma_f32_16x16x32_bf16 v[58:61], v[150:153], v[198:201], v[58:61]
	v_mfma_f32_16x16x32_bf16 v[78:81], v[150:153], v[190:193], v[78:81]
	v_mfma_f32_16x16x32_bf16 v[78:81], v[154:157], v[194:197], v[78:81]
	v_mfma_f32_16x16x32_bf16 v[90:93], v[154:157], v[186:189], v[90:93]
	v_mfma_f32_16x16x32_bf16 v[90:93], v[150:153], v[182:185], v[90:93]
	v_mfma_f32_16x16x32_bf16 v[30:33], v[158:161], v[182:185], v[30:33]
	v_mfma_f32_16x16x32_bf16 v[30:33], v[162:165], v[186:189], v[30:33]
	v_mfma_f32_16x16x32_bf16 v[22:25], v[162:165], v[194:197], v[22:25]
	v_mfma_f32_16x16x32_bf16 v[22:25], v[158:161], v[190:193], v[22:25]
	v_mfma_f32_16x16x32_bf16 v[14:17], v[158:161], v[198:201], v[14:17]
	v_mfma_f32_16x16x32_bf16 v[14:17], v[162:165], v[202:205], v[14:17]
	v_mfma_f32_16x16x32_bf16 v[6:9], v[162:165], v[210:213], v[6:9]
	v_mfma_f32_16x16x32_bf16 v[6:9], v[158:161], v[206:209], v[6:9]
	v_mfma_f32_16x16x32_bf16 v[2:5], v[174:177], v[206:209], v[2:5]
	v_mfma_f32_16x16x32_bf16 v[2:5], v[178:181], v[210:213], v[2:5]
	v_mfma_f32_16x16x32_bf16 v[10:13], v[178:181], v[202:205], v[10:13]
	v_mfma_f32_16x16x32_bf16 v[10:13], v[174:177], v[198:201], v[10:13]
	v_mfma_f32_16x16x32_bf16 v[18:21], v[174:177], v[190:193], v[18:21]
	v_mfma_f32_16x16x32_bf16 v[18:21], v[178:181], v[194:197], v[18:21]
	v_mfma_f32_16x16x32_bf16 v[26:29], v[178:181], v[186:189], v[26:29]
	v_mfma_f32_16x16x32_bf16 v[26:29], v[174:177], v[182:185], v[26:29]
	s_barrier
	s_add_i32 s58, s58, 2
	s_add_u32 s40, s40, 0x100
	s_addc_u32 s41, s41, 0
	s_add_u32 s56, s56, 0x100
	s_addc_u32 s57, s57, 0
	s_cmp_gt_u32 s58, 13
	s_cbranch_scc1 .Lpeel_done_160
.LBB0_160:
	s_add_u32 s26, s40, 0xfffc0080
	s_addc_u32 s27, s41, -1
	s_add_i32 s59, 0, 0x10000
	s_cmp_eq_u32 s58, 12
	s_cselect_b32 vcc_hi, s29, s27
	s_cselect_b32 vcc_lo, s43, s26
	v_add_u32_e32 v0, s59, v167
	s_cselect_b32 s27, s21, s57
	s_cselect_b32 s26, s55, s56
	s_add_i32 s62, 0, 0x14000
	ds_read_b128 v[142:145], v0
	ds_read_b128 v[146:149], v0 offset:1024
	ds_read_b128 v[150:153], v0 offset:2048
	ds_read_b128 v[154:157], v0 offset:3072
	v_add_u32_e32 v0, s62, v167
	ds_read_b128 v[158:161], v0
	ds_read_b128 v[162:165], v0 offset:1024
	ds_read_b128 v[174:177], v0 offset:2048
	ds_read_b128 v[178:181], v0 offset:3072
	v_lshl_add_u64 v[214:215], s[40:41], 0, v[138:139]
	s_add_i32 m0, s23, 0xc000
	ds_read_b128 v[182:185], v173
	ds_read_b128 v[186:189], v173 offset:1024
	ds_read_b128 v[190:193], v173 offset:2048
	ds_read_b128 v[194:197], v173 offset:3072
	ds_read_b128 v[198:201], v173 offset:4096
	ds_read_b128 v[202:205], v173 offset:5120
	ds_read_b128 v[206:209], v173 offset:6144
	ds_read_b128 v[210:213], v173 offset:7168
	global_load_lds_dwordx4 v[214:215], off
	v_lshl_add_u64 v[214:215], s[40:41], 0, v[140:141]
	s_add_i32 m0, s23, 0xe000
	s_nop 0
	global_load_lds_dwordx4 v[214:215], off
	s_waitcnt vmcnt(8)
	s_waitcnt lgkmcnt(0)
	s_barrier
	s_waitcnt lgkmcnt(0)
	v_mfma_f32_16x16x32_bf16 v[126:129], v[142:145], v[182:185], v[126:129]
	v_mfma_f32_16x16x32_bf16 v[126:129], v[146:149], v[186:189], v[126:129]
	v_mfma_f32_16x16x32_bf16 v[118:121], v[146:149], v[194:197], v[118:121]
	v_mfma_f32_16x16x32_bf16 v[118:121], v[142:145], v[190:193], v[118:121]
	v_mfma_f32_16x16x32_bf16 v[110:113], v[142:145], v[198:201], v[110:113]
	v_mfma_f32_16x16x32_bf16 v[110:113], v[146:149], v[202:205], v[110:113]
	v_mfma_f32_16x16x32_bf16 v[102:105], v[146:149], v[210:213], v[102:105]
	v_mfma_f32_16x16x32_bf16 v[102:105], v[142:145], v[206:209], v[102:105]
	v_mfma_f32_16x16x32_bf16 v[98:101], v[150:153], v[206:209], v[98:101]
	v_mfma_f32_16x16x32_bf16 v[98:101], v[154:157], v[210:213], v[98:101]
	v_mfma_f32_16x16x32_bf16 v[106:109], v[154:157], v[202:205], v[106:109]
	v_mfma_f32_16x16x32_bf16 v[106:109], v[150:153], v[198:201], v[106:109]
	v_mfma_f32_16x16x32_bf16 v[114:117], v[150:153], v[190:193], v[114:117]
	v_mfma_f32_16x16x32_bf16 v[114:117], v[154:157], v[194:197], v[114:117]
	v_mfma_f32_16x16x32_bf16 v[122:125], v[154:157], v[186:189], v[122:125]
	v_mfma_f32_16x16x32_bf16 v[122:125], v[150:153], v[182:185], v[122:125]
	v_mfma_f32_16x16x32_bf16 v[82:85], v[158:161], v[182:185], v[82:85]
	v_mfma_f32_16x16x32_bf16 v[82:85], v[162:165], v[186:189], v[82:85]
	v_mfma_f32_16x16x32_bf16 v[70:73], v[162:165], v[194:197], v[70:73]
	v_mfma_f32_16x16x32_bf16 v[70:73], v[158:161], v[190:193], v[70:73]
	v_mfma_f32_16x16x32_bf16 v[54:57], v[158:161], v[198:201], v[54:57]
	v_mfma_f32_16x16x32_bf16 v[54:57], v[162:165], v[202:205], v[54:57]
	v_mfma_f32_16x16x32_bf16 v[38:41], v[162:165], v[210:213], v[38:41]
	v_mfma_f32_16x16x32_bf16 v[38:41], v[158:161], v[206:209], v[38:41]
	v_mfma_f32_16x16x32_bf16 v[34:37], v[174:177], v[206:209], v[34:37]
	v_mfma_f32_16x16x32_bf16 v[34:37], v[178:181], v[210:213], v[34:37]
	v_mfma_f32_16x16x32_bf16 v[46:49], v[178:181], v[202:205], v[46:49]
	v_mfma_f32_16x16x32_bf16 v[46:49], v[174:177], v[198:201], v[46:49]
	v_mfma_f32_16x16x32_bf16 v[62:65], v[174:177], v[190:193], v[62:65]
	v_mfma_f32_16x16x32_bf16 v[62:65], v[178:181], v[194:197], v[62:65]
	v_mfma_f32_16x16x32_bf16 v[74:77], v[178:181], v[186:189], v[74:77]
	v_mfma_f32_16x16x32_bf16 v[74:77], v[174:177], v[182:185], v[74:77]
	s_barrier
	s_add_i32 s59, s59, s44
	v_lshl_add_u64 v[214:215], s[26:27], 0, v[132:133]
	s_mov_b32 m0, s59
	ds_read_b128 v[182:185], v173 offset:16384
	ds_read_b128 v[186:189], v173 offset:17408
	ds_read_b128 v[190:193], v173 offset:18432
	ds_read_b128 v[194:197], v173 offset:19456
	ds_read_b128 v[198:201], v173 offset:20480
	ds_read_b128 v[202:205], v173 offset:21504
	ds_read_b128 v[206:209], v173 offset:22528
	ds_read_b128 v[210:213], v173 offset:23552
	global_load_lds_dwordx4 v[214:215], off
	s_add_i32 m0, s59, 0x2000
	s_add_u32 s60, s26, 0x40000
	v_lshl_add_u64 v[216:217], s[26:27], 0, v[136:137]
	s_addc_u32 s61, s27, 0
	s_add_i32 s59, s62, s44
	global_load_lds_dwordx4 v[216:217], off
	v_lshl_add_u64 v[218:219], s[60:61], 0, v[132:133]
	s_mov_b32 m0, s59
	v_lshl_add_u64 v[220:221], vcc, 0, v[134:135]
	global_load_lds_dwordx4 v[218:219], off
	v_lshl_add_u64 v[218:219], s[60:61], 0, v[136:137]
	s_add_i32 m0, s59, 0x2000
	s_nop 0
	global_load_lds_dwordx4 v[218:219], off
	v_lshl_add_u64 v[218:219], vcc, 0, v[130:131]
	s_mov_b32 m0, s23
	s_nop 0
	global_load_lds_dwordx4 v[218:219], off
	s_mov_b32 m0, s45
	s_nop 0
	global_load_lds_dwordx4 v[220:221], off
	s_waitcnt vmcnt(8)
	s_waitcnt lgkmcnt(0)
	s_barrier
	s_waitcnt lgkmcnt(0)
	v_mfma_f32_16x16x32_bf16 v[94:97], v[142:145], v[182:185], v[94:97]
	v_mfma_f32_16x16x32_bf16 v[94:97], v[146:149], v[186:189], v[94:97]
	v_mfma_f32_16x16x32_bf16 v[86:89], v[146:149], v[194:197], v[86:89]
	v_mfma_f32_16x16x32_bf16 v[86:89], v[142:145], v[190:193], v[86:89]
	v_mfma_f32_16x16x32_bf16 v[66:69], v[142:145], v[198:201], v[66:69]
	v_mfma_f32_16x16x32_bf16 v[66:69], v[146:149], v[202:205], v[66:69]
	v_mfma_f32_16x16x32_bf16 v[50:53], v[146:149], v[210:213], v[50:53]
	v_mfma_f32_16x16x32_bf16 v[50:53], v[142:145], v[206:209], v[50:53]
	v_mfma_f32_16x16x32_bf16 v[42:45], v[150:153], v[206:209], v[42:45]
	v_mfma_f32_16x16x32_bf16 v[42:45], v[154:157], v[210:213], v[42:45]
	v_mfma_f32_16x16x32_bf16 v[58:61], v[154:157], v[202:205], v[58:61]
	v_mfma_f32_16x16x32_bf16 v[58:61], v[150:153], v[198:201], v[58:61]
	v_mfma_f32_16x16x32_bf16 v[78:81], v[150:153], v[190:193], v[78:81]
	v_mfma_f32_16x16x32_bf16 v[78:81], v[154:157], v[194:197], v[78:81]
	v_mfma_f32_16x16x32_bf16 v[90:93], v[154:157], v[186:189], v[90:93]
	v_mfma_f32_16x16x32_bf16 v[90:93], v[150:153], v[182:185], v[90:93]
	v_mfma_f32_16x16x32_bf16 v[30:33], v[158:161], v[182:185], v[30:33]
	v_mfma_f32_16x16x32_bf16 v[30:33], v[162:165], v[186:189], v[30:33]
	v_mfma_f32_16x16x32_bf16 v[22:25], v[162:165], v[194:197], v[22:25]
	v_mfma_f32_16x16x32_bf16 v[22:25], v[158:161], v[190:193], v[22:25]
	v_mfma_f32_16x16x32_bf16 v[14:17], v[158:161], v[198:201], v[14:17]
	v_mfma_f32_16x16x32_bf16 v[14:17], v[162:165], v[202:205], v[14:17]
	v_mfma_f32_16x16x32_bf16 v[6:9], v[162:165], v[210:213], v[6:9]
	v_mfma_f32_16x16x32_bf16 v[6:9], v[158:161], v[206:209], v[6:9]
	v_mfma_f32_16x16x32_bf16 v[2:5], v[174:177], v[206:209], v[2:5]
	v_mfma_f32_16x16x32_bf16 v[2:5], v[178:181], v[210:213], v[2:5]
	v_mfma_f32_16x16x32_bf16 v[10:13], v[178:181], v[202:205], v[10:13]
	v_mfma_f32_16x16x32_bf16 v[10:13], v[174:177], v[198:201], v[10:13]
	v_mfma_f32_16x16x32_bf16 v[18:21], v[174:177], v[190:193], v[18:21]
	v_mfma_f32_16x16x32_bf16 v[18:21], v[178:181], v[194:197], v[18:21]
	v_mfma_f32_16x16x32_bf16 v[26:29], v[178:181], v[186:189], v[26:29]
	v_mfma_f32_16x16x32_bf16 v[26:29], v[174:177], v[182:185], v[26:29]
	s_barrier
	s_add_i32 s59, 0, 0x18000
	v_add_u32_e32 v0, s59, v167
	s_add_i32 s62, 0, 0x1c000
	ds_read_b128 v[142:145], v0
	ds_read_b128 v[146:149], v0 offset:1024
	ds_read_b128 v[150:153], v0 offset:2048
	ds_read_b128 v[154:157], v0 offset:3072
	v_add_u32_e32 v0, s62, v167
	ds_read_b128 v[158:161], v0
	ds_read_b128 v[162:165], v0 offset:1024
	ds_read_b128 v[174:177], v0 offset:2048
	ds_read_b128 v[178:181], v0 offset:3072
	s_add_u32 s60, vcc_lo, 0x40000
	s_addc_u32 s61, vcc_hi, 0
	s_mov_b32 m0, s47
	v_lshl_add_u64 v[222:223], s[60:61], 0, v[130:131]
	ds_read_b128 v[182:185], v173 offset:32768
	ds_read_b128 v[186:189], v173 offset:33792
	ds_read_b128 v[190:193], v173 offset:34816
	ds_read_b128 v[194:197], v173 offset:35840
	ds_read_b128 v[198:201], v173 offset:36864
	ds_read_b128 v[202:205], v173 offset:37888
	ds_read_b128 v[206:209], v173 offset:38912
	ds_read_b128 v[210:213], v173 offset:39936
	global_load_lds_dwordx4 v[222:223], off
	v_lshl_add_u64 v[222:223], s[60:61], 0, v[134:135]
	s_mov_b32 m0, s49
	s_nop 0
	global_load_lds_dwordx4 v[222:223], off
	s_waitcnt vmcnt(8)
	s_waitcnt lgkmcnt(0)
	s_barrier
	s_waitcnt lgkmcnt(0)
	v_mfma_f32_16x16x32_bf16 v[126:129], v[142:145], v[182:185], v[126:129]
	v_mfma_f32_16x16x32_bf16 v[126:129], v[146:149], v[186:189], v[126:129]
	v_mfma_f32_16x16x32_bf16 v[118:121], v[146:149], v[194:197], v[118:121]
	v_mfma_f32_16x16x32_bf16 v[118:121], v[142:145], v[190:193], v[118:121]
	v_mfma_f32_16x16x32_bf16 v[110:113], v[142:145], v[198:201], v[110:113]
	v_mfma_f32_16x16x32_bf16 v[110:113], v[146:149], v[202:205], v[110:113]
	v_mfma_f32_16x16x32_bf16 v[102:105], v[146:149], v[210:213], v[102:105]
	v_mfma_f32_16x16x32_bf16 v[102:105], v[142:145], v[206:209], v[102:105]
	v_mfma_f32_16x16x32_bf16 v[98:101], v[150:153], v[206:209], v[98:101]
	v_mfma_f32_16x16x32_bf16 v[98:101], v[154:157], v[210:213], v[98:101]
	v_mfma_f32_16x16x32_bf16 v[106:109], v[154:157], v[202:205], v[106:109]
	v_mfma_f32_16x16x32_bf16 v[106:109], v[150:153], v[198:201], v[106:109]
	v_mfma_f32_16x16x32_bf16 v[114:117], v[150:153], v[190:193], v[114:117]
	v_mfma_f32_16x16x32_bf16 v[114:117], v[154:157], v[194:197], v[114:117]
	v_mfma_f32_16x16x32_bf16 v[122:125], v[154:157], v[186:189], v[122:125]
	v_mfma_f32_16x16x32_bf16 v[122:125], v[150:153], v[182:185], v[122:125]
	v_mfma_f32_16x16x32_bf16 v[82:85], v[158:161], v[182:185], v[82:85]
	v_mfma_f32_16x16x32_bf16 v[82:85], v[162:165], v[186:189], v[82:85]
	v_mfma_f32_16x16x32_bf16 v[70:73], v[162:165], v[194:197], v[70:73]
	v_mfma_f32_16x16x32_bf16 v[70:73], v[158:161], v[190:193], v[70:73]
	v_mfma_f32_16x16x32_bf16 v[54:57], v[158:161], v[198:201], v[54:57]
	v_mfma_f32_16x16x32_bf16 v[54:57], v[162:165], v[202:205], v[54:57]
	v_mfma_f32_16x16x32_bf16 v[38:41], v[162:165], v[210:213], v[38:41]
	v_mfma_f32_16x16x32_bf16 v[38:41], v[158:161], v[206:209], v[38:41]
	v_mfma_f32_16x16x32_bf16 v[34:37], v[174:177], v[206:209], v[34:37]
	v_mfma_f32_16x16x32_bf16 v[34:37], v[178:181], v[210:213], v[34:37]
	v_mfma_f32_16x16x32_bf16 v[46:49], v[178:181], v[202:205], v[46:49]
	v_mfma_f32_16x16x32_bf16 v[46:49], v[174:177], v[198:201], v[46:49]
	v_mfma_f32_16x16x32_bf16 v[62:65], v[174:177], v[190:193], v[62:65]
	v_mfma_f32_16x16x32_bf16 v[62:65], v[178:181], v[194:197], v[62:65]
	v_mfma_f32_16x16x32_bf16 v[74:77], v[178:181], v[186:189], v[74:77]
	v_mfma_f32_16x16x32_bf16 v[74:77], v[174:177], v[182:185], v[74:77]
	s_barrier
	s_add_i32 s59, s59, s44
	v_lshl_add_u64 v[214:215], v[214:215], 0, s[98:99]
	s_mov_b32 m0, s59
	ds_read_b128 v[182:185], v173 offset:49152
	ds_read_b128 v[186:189], v173 offset:50176
	ds_read_b128 v[190:193], v173 offset:51200
	ds_read_b128 v[194:197], v173 offset:52224
	ds_read_b128 v[198:201], v173 offset:53248
	ds_read_b128 v[202:205], v173 offset:54272
	ds_read_b128 v[206:209], v173 offset:55296
	ds_read_b128 v[210:213], v173 offset:56320
	global_load_lds_dwordx4 v[214:215], off
	s_add_i32 m0, s59, 0x2000
	s_add_u32 s26, s26, 0x40080
	v_lshl_add_u64 v[214:215], v[216:217], 0, s[98:99]
	s_addc_u32 s27, s27, 0
	s_add_i32 s59, s62, s44
	global_load_lds_dwordx4 v[214:215], off
	v_lshl_add_u64 v[214:215], s[26:27], 0, v[132:133]
	s_mov_b32 m0, s59
	s_nop 0
	global_load_lds_dwordx4 v[214:215], off
	v_lshl_add_u64 v[214:215], s[26:27], 0, v[136:137]
	s_add_i32 m0, s59, 0x2000
	s_nop 0
	global_load_lds_dwordx4 v[214:215], off
	v_lshl_add_u64 v[214:215], v[218:219], 0, s[98:99]
	s_mov_b32 m0, s52
	s_nop 0
	global_load_lds_dwordx4 v[214:215], off
	v_lshl_add_u64 v[214:215], v[220:221], 0, s[98:99]
	s_mov_b32 m0, s53
	s_nop 0
	global_load_lds_dwordx4 v[214:215], off
	s_waitcnt vmcnt(8)
	s_waitcnt lgkmcnt(0)
	s_barrier
	s_waitcnt lgkmcnt(0)
	v_mfma_f32_16x16x32_bf16 v[94:97], v[142:145], v[182:185], v[94:97]
	v_mfma_f32_16x16x32_bf16 v[94:97], v[146:149], v[186:189], v[94:97]
	v_mfma_f32_16x16x32_bf16 v[86:89], v[146:149], v[194:197], v[86:89]
	v_mfma_f32_16x16x32_bf16 v[86:89], v[142:145], v[190:193], v[86:89]
	v_mfma_f32_16x16x32_bf16 v[66:69], v[142:145], v[198:201], v[66:69]
	v_mfma_f32_16x16x32_bf16 v[66:69], v[146:149], v[202:205], v[66:69]
	v_mfma_f32_16x16x32_bf16 v[50:53], v[146:149], v[210:213], v[50:53]
	v_mfma_f32_16x16x32_bf16 v[50:53], v[142:145], v[206:209], v[50:53]
	v_mfma_f32_16x16x32_bf16 v[42:45], v[150:153], v[206:209], v[42:45]
	v_mfma_f32_16x16x32_bf16 v[42:45], v[154:157], v[210:213], v[42:45]
	v_mfma_f32_16x16x32_bf16 v[58:61], v[154:157], v[202:205], v[58:61]
	v_mfma_f32_16x16x32_bf16 v[58:61], v[150:153], v[198:201], v[58:61]
	v_mfma_f32_16x16x32_bf16 v[78:81], v[150:153], v[190:193], v[78:81]
	v_mfma_f32_16x16x32_bf16 v[78:81], v[154:157], v[194:197], v[78:81]
	v_mfma_f32_16x16x32_bf16 v[90:93], v[154:157], v[186:189], v[90:93]
	v_mfma_f32_16x16x32_bf16 v[90:93], v[150:153], v[182:185], v[90:93]
	v_mfma_f32_16x16x32_bf16 v[30:33], v[158:161], v[182:185], v[30:33]
	v_mfma_f32_16x16x32_bf16 v[30:33], v[162:165], v[186:189], v[30:33]
	v_mfma_f32_16x16x32_bf16 v[22:25], v[162:165], v[194:197], v[22:25]
	v_mfma_f32_16x16x32_bf16 v[22:25], v[158:161], v[190:193], v[22:25]
	v_mfma_f32_16x16x32_bf16 v[14:17], v[158:161], v[198:201], v[14:17]
	v_mfma_f32_16x16x32_bf16 v[14:17], v[162:165], v[202:205], v[14:17]
	v_mfma_f32_16x16x32_bf16 v[6:9], v[162:165], v[210:213], v[6:9]
	v_mfma_f32_16x16x32_bf16 v[6:9], v[158:161], v[206:209], v[6:9]
	v_mfma_f32_16x16x32_bf16 v[2:5], v[174:177], v[206:209], v[2:5]
	v_mfma_f32_16x16x32_bf16 v[2:5], v[178:181], v[210:213], v[2:5]
	v_mfma_f32_16x16x32_bf16 v[10:13], v[178:181], v[202:205], v[10:13]
	v_mfma_f32_16x16x32_bf16 v[10:13], v[174:177], v[198:201], v[10:13]
	v_mfma_f32_16x16x32_bf16 v[18:21], v[174:177], v[190:193], v[18:21]
	v_mfma_f32_16x16x32_bf16 v[18:21], v[178:181], v[194:197], v[18:21]
	v_mfma_f32_16x16x32_bf16 v[26:29], v[178:181], v[186:189], v[26:29]
	v_mfma_f32_16x16x32_bf16 v[26:29], v[174:177], v[182:185], v[26:29]
	s_barrier
	s_add_i32 s58, s58, 2
	s_add_u32 s40, s40, 0x100
	s_addc_u32 s41, s41, 0
	s_add_u32 s56, s56, 0x100
	s_addc_u32 s57, s57, 0
	s_cmp_gt_u32 s58, 13
	s_cbranch_scc0 .LBB0_160

.LBB0_216:
	s_add_i32 s13, s61, -2
	s_add_u32 s28, s28, 0x80
	s_addc_u32 s29, s29, 0
	s_add_u32 s23, s40, 0x100
	s_addc_u32 s40, s41, 0
	s_mov_b32 s30, 0
	s_add_i32 s41, s30, 2
	s_add_u32 vcc_lo, s28, 0x80
	s_addc_u32 s31, s29, 0
	s_add_i32 s62, 0, 0x10000
	s_cmp_eq_u32 s13, s30
	s_cselect_b32 s31, s25, s31
	s_cselect_b32 s30, s24, vcc_lo
	v_add_u32_e32 v145, s62, v175
	s_cselect_b32 vcc_hi, s27, s40
	s_cselect_b32 vcc_lo, s26, s23
	s_add_i32 s63, 0, 0x14000
	ds_read_b128 v[130:133], v145
	ds_read_b128 v[134:137], v145 offset:1024
	ds_read_b128 v[152:155], v145 offset:2048
	ds_read_b128 v[156:159], v145 offset:3072
	v_add_u32_e32 v145, s63, v175
	ds_read_b128 v[160:163], v145
	ds_read_b128 v[164:167], v145 offset:1024
	ds_read_b128 v[168:171], v145 offset:2048
	ds_read_b128 v[186:189], v145 offset:3072
	v_lshl_add_u64 v[172:173], s[28:29], 0, v[148:149]
	s_add_i32 m0, s93, 0xc000
	ds_read_b128 v[190:193], v184
	ds_read_b128 v[194:197], v184 offset:1024
	ds_read_b128 v[198:201], v184 offset:2048
	ds_read_b128 v[202:205], v184 offset:3072
	ds_read_b128 v[206:209], v184 offset:4096
	ds_read_b128 v[210:213], v184 offset:5120
	ds_read_b128 v[214:217], v184 offset:6144
	ds_read_b128 v[218:221], v184 offset:7168
	global_load_lds_dwordx4 v[172:173], off
	v_lshl_add_u64 v[172:173], s[28:29], 0, v[150:151]
	s_add_i32 m0, s93, 0xe000
	s_nop 0
	global_load_lds_dwordx4 v[172:173], off
	s_waitcnt vmcnt(8)
	s_waitcnt lgkmcnt(0)
	s_barrier
	s_waitcnt lgkmcnt(0)
	v_mfma_f32_16x16x32_bf16 v[126:129], v[130:133], v[190:193], 0
	v_mfma_f32_16x16x32_bf16 v[126:129], v[134:137], v[194:197], v[126:129]
	v_mfma_f32_16x16x32_bf16 v[110:113], v[134:137], v[202:205], 0
	v_mfma_f32_16x16x32_bf16 v[110:113], v[130:133], v[198:201], v[110:113]
	v_mfma_f32_16x16x32_bf16 v[94:97], v[130:133], v[206:209], 0
	v_mfma_f32_16x16x32_bf16 v[94:97], v[134:137], v[210:213], v[94:97]
	v_mfma_f32_16x16x32_bf16 v[78:81], v[134:137], v[218:221], 0
	v_mfma_f32_16x16x32_bf16 v[78:81], v[130:133], v[214:217], v[78:81]
	v_mfma_f32_16x16x32_bf16 v[74:77], v[152:155], v[214:217], 0
	v_mfma_f32_16x16x32_bf16 v[74:77], v[156:159], v[218:221], v[74:77]
	v_mfma_f32_16x16x32_bf16 v[90:93], v[156:159], v[210:213], 0
	v_mfma_f32_16x16x32_bf16 v[90:93], v[152:155], v[206:209], v[90:93]
	v_mfma_f32_16x16x32_bf16 v[106:109], v[152:155], v[198:201], 0
	v_mfma_f32_16x16x32_bf16 v[106:109], v[156:159], v[202:205], v[106:109]
	v_mfma_f32_16x16x32_bf16 v[122:125], v[156:159], v[194:197], 0
	v_mfma_f32_16x16x32_bf16 v[122:125], v[152:155], v[190:193], v[122:125]
	v_mfma_f32_16x16x32_bf16 v[118:121], v[160:163], v[190:193], 0
	v_mfma_f32_16x16x32_bf16 v[118:121], v[164:167], v[194:197], v[118:121]
	v_mfma_f32_16x16x32_bf16 v[102:105], v[164:167], v[202:205], 0
	v_mfma_f32_16x16x32_bf16 v[102:105], v[160:163], v[198:201], v[102:105]
	v_mfma_f32_16x16x32_bf16 v[86:89], v[160:163], v[206:209], 0
	v_mfma_f32_16x16x32_bf16 v[86:89], v[164:167], v[210:213], v[86:89]
	v_mfma_f32_16x16x32_bf16 v[70:73], v[164:167], v[218:221], 0
	v_mfma_f32_16x16x32_bf16 v[70:73], v[160:163], v[214:217], v[70:73]
	v_mfma_f32_16x16x32_bf16 v[66:69], v[168:171], v[214:217], 0
	v_mfma_f32_16x16x32_bf16 v[66:69], v[186:189], v[218:221], v[66:69]
	v_mfma_f32_16x16x32_bf16 v[82:85], v[186:189], v[210:213], 0
	v_mfma_f32_16x16x32_bf16 v[82:85], v[168:171], v[206:209], v[82:85]
	v_mfma_f32_16x16x32_bf16 v[98:101], v[168:171], v[198:201], 0
	v_mfma_f32_16x16x32_bf16 v[98:101], v[186:189], v[202:205], v[98:101]
	v_mfma_f32_16x16x32_bf16 v[114:117], v[186:189], v[194:197], 0
	v_mfma_f32_16x16x32_bf16 v[114:117], v[168:171], v[190:193], v[114:117]
	s_barrier
	s_add_i32 s62, s62, s49
	v_lshl_add_u64 v[172:173], vcc, 0, v[0:1]
	s_mov_b32 m0, s62
	ds_read_b128 v[190:193], v184 offset:16384
	ds_read_b128 v[194:197], v184 offset:17408
	ds_read_b128 v[198:201], v184 offset:18432
	ds_read_b128 v[202:205], v184 offset:19456
	ds_read_b128 v[206:209], v184 offset:20480
	ds_read_b128 v[210:213], v184 offset:21504
	ds_read_b128 v[214:217], v184 offset:22528
	ds_read_b128 v[218:221], v184 offset:23552
	global_load_lds_dwordx4 v[172:173], off
	s_add_i32 m0, s62, 0x2000
	v_lshl_add_u64 v[222:223], vcc, 0, v[142:143]
	s_add_u32 vcc_lo, vcc_lo, s96
	s_addc_u32 vcc_hi, vcc_hi, 0
	s_add_i32 s62, s63, s49
	global_load_lds_dwordx4 v[222:223], off
	v_lshl_add_u64 v[236:237], vcc, 0, v[0:1]
	s_mov_b32 m0, s62
	v_lshl_add_u64 v[238:239], vcc, 0, v[142:143]
	global_load_lds_dwordx4 v[236:237], off
	s_add_i32 m0, s62, 0x2000
	v_lshl_add_u64 v[240:241], s[30:31], 0, v[138:139]
	global_load_lds_dwordx4 v[238:239], off
	s_mov_b32 m0, s93
	v_lshl_add_u64 v[242:243], s[30:31], 0, v[140:141]
	global_load_lds_dwordx4 v[240:241], off
	s_mov_b32 m0, s88
	s_nop 0
	global_load_lds_dwordx4 v[242:243], off
	s_waitcnt vmcnt(8)
	s_waitcnt lgkmcnt(0)
	s_barrier
	s_waitcnt lgkmcnt(0)
	v_mfma_f32_16x16x32_bf16 v[62:65], v[130:133], v[190:193], 0
	v_mfma_f32_16x16x32_bf16 v[62:65], v[134:137], v[194:197], v[62:65]
	v_mfma_f32_16x16x32_bf16 v[46:49], v[134:137], v[202:205], 0
	v_mfma_f32_16x16x32_bf16 v[46:49], v[130:133], v[198:201], v[46:49]
	v_mfma_f32_16x16x32_bf16 v[30:33], v[130:133], v[206:209], 0
	v_mfma_f32_16x16x32_bf16 v[30:33], v[134:137], v[210:213], v[30:33]
	v_mfma_f32_16x16x32_bf16 v[14:17], v[134:137], v[218:221], 0
	v_mfma_f32_16x16x32_bf16 v[14:17], v[130:133], v[214:217], v[14:17]
	v_mfma_f32_16x16x32_bf16 v[10:13], v[152:155], v[214:217], 0
	v_mfma_f32_16x16x32_bf16 v[10:13], v[156:159], v[218:221], v[10:13]
	v_mfma_f32_16x16x32_bf16 v[26:29], v[156:159], v[210:213], 0
	v_mfma_f32_16x16x32_bf16 v[26:29], v[152:155], v[206:209], v[26:29]
	v_mfma_f32_16x16x32_bf16 v[42:45], v[152:155], v[198:201], 0
	v_mfma_f32_16x16x32_bf16 v[42:45], v[156:159], v[202:205], v[42:45]
	v_mfma_f32_16x16x32_bf16 v[58:61], v[156:159], v[194:197], 0
	v_mfma_f32_16x16x32_bf16 v[58:61], v[152:155], v[190:193], v[58:61]
	v_mfma_f32_16x16x32_bf16 v[54:57], v[160:163], v[190:193], 0
	v_mfma_f32_16x16x32_bf16 v[54:57], v[164:167], v[194:197], v[54:57]
	v_mfma_f32_16x16x32_bf16 v[38:41], v[164:167], v[202:205], 0
	v_mfma_f32_16x16x32_bf16 v[38:41], v[160:163], v[198:201], v[38:41]
	v_mfma_f32_16x16x32_bf16 v[22:25], v[160:163], v[206:209], 0
	v_mfma_f32_16x16x32_bf16 v[22:25], v[164:167], v[210:213], v[22:25]
	v_mfma_f32_16x16x32_bf16 v[6:9], v[164:167], v[218:221], 0
	v_mfma_f32_16x16x32_bf16 v[6:9], v[160:163], v[214:217], v[6:9]
	v_mfma_f32_16x16x32_bf16 v[2:5], v[168:171], v[214:217], 0
	v_mfma_f32_16x16x32_bf16 v[2:5], v[186:189], v[218:221], v[2:5]
	v_mfma_f32_16x16x32_bf16 v[18:21], v[186:189], v[210:213], 0
	v_mfma_f32_16x16x32_bf16 v[18:21], v[168:171], v[206:209], v[18:21]
	v_mfma_f32_16x16x32_bf16 v[34:37], v[168:171], v[198:201], 0
	v_mfma_f32_16x16x32_bf16 v[34:37], v[186:189], v[202:205], v[34:37]
	v_mfma_f32_16x16x32_bf16 v[50:53], v[186:189], v[194:197], 0
	v_mfma_f32_16x16x32_bf16 v[50:53], v[168:171], v[190:193], v[50:53]
	s_barrier
	s_add_i32 s62, 0, 0x18000
	v_add_u32_e32 v145, s62, v175
	s_add_i32 s63, 0, 0x1c000
	ds_read_b128 v[130:133], v145
	ds_read_b128 v[134:137], v145 offset:1024
	ds_read_b128 v[152:155], v145 offset:2048
	ds_read_b128 v[156:159], v145 offset:3072
	v_add_u32_e32 v145, s63, v175
	ds_read_b128 v[160:163], v145
	ds_read_b128 v[164:167], v145 offset:1024
	ds_read_b128 v[168:171], v145 offset:2048
	ds_read_b128 v[186:189], v145 offset:3072
	s_add_u32 s30, s30, s96
	s_addc_u32 s31, s31, 0
	s_mov_b32 m0, s89
	v_lshl_add_u64 v[244:245], s[30:31], 0, v[138:139]
	ds_read_b128 v[190:193], v184 offset:32768
	ds_read_b128 v[194:197], v184 offset:33792
	ds_read_b128 v[198:201], v184 offset:34816
	ds_read_b128 v[202:205], v184 offset:35840
	ds_read_b128 v[206:209], v184 offset:36864
	ds_read_b128 v[210:213], v184 offset:37888
	ds_read_b128 v[214:217], v184 offset:38912
	ds_read_b128 v[218:221], v184 offset:39936
	global_load_lds_dwordx4 v[244:245], off
	v_lshl_add_u64 v[244:245], s[30:31], 0, v[140:141]
	s_mov_b32 m0, s52
	s_nop 0
	global_load_lds_dwordx4 v[244:245], off
	s_waitcnt vmcnt(8)
	s_waitcnt lgkmcnt(0)
	s_barrier
	s_waitcnt lgkmcnt(0)
	v_mfma_f32_16x16x32_bf16 v[126:129], v[130:133], v[190:193], v[126:129]
	v_mfma_f32_16x16x32_bf16 v[126:129], v[134:137], v[194:197], v[126:129]
	v_mfma_f32_16x16x32_bf16 v[110:113], v[134:137], v[202:205], v[110:113]
	v_mfma_f32_16x16x32_bf16 v[110:113], v[130:133], v[198:201], v[110:113]
	v_mfma_f32_16x16x32_bf16 v[94:97], v[130:133], v[206:209], v[94:97]
	v_mfma_f32_16x16x32_bf16 v[94:97], v[134:137], v[210:213], v[94:97]
	v_mfma_f32_16x16x32_bf16 v[78:81], v[134:137], v[218:221], v[78:81]
	v_mfma_f32_16x16x32_bf16 v[78:81], v[130:133], v[214:217], v[78:81]
	v_mfma_f32_16x16x32_bf16 v[74:77], v[152:155], v[214:217], v[74:77]
	v_mfma_f32_16x16x32_bf16 v[74:77], v[156:159], v[218:221], v[74:77]
	v_mfma_f32_16x16x32_bf16 v[90:93], v[156:159], v[210:213], v[90:93]
	v_mfma_f32_16x16x32_bf16 v[90:93], v[152:155], v[206:209], v[90:93]
	v_mfma_f32_16x16x32_bf16 v[106:109], v[152:155], v[198:201], v[106:109]
	v_mfma_f32_16x16x32_bf16 v[106:109], v[156:159], v[202:205], v[106:109]
	v_mfma_f32_16x16x32_bf16 v[122:125], v[156:159], v[194:197], v[122:125]
	v_mfma_f32_16x16x32_bf16 v[122:125], v[152:155], v[190:193], v[122:125]
	v_mfma_f32_16x16x32_bf16 v[118:121], v[160:163], v[190:193], v[118:121]
	v_mfma_f32_16x16x32_bf16 v[118:121], v[164:167], v[194:197], v[118:121]
	v_mfma_f32_16x16x32_bf16 v[102:105], v[164:167], v[202:205], v[102:105]
	v_mfma_f32_16x16x32_bf16 v[102:105], v[160:163], v[198:201], v[102:105]
	v_mfma_f32_16x16x32_bf16 v[86:89], v[160:163], v[206:209], v[86:89]
	v_mfma_f32_16x16x32_bf16 v[86:89], v[164:167], v[210:213], v[86:89]
	v_mfma_f32_16x16x32_bf16 v[70:73], v[164:167], v[218:221], v[70:73]
	v_mfma_f32_16x16x32_bf16 v[70:73], v[160:163], v[214:217], v[70:73]
	v_mfma_f32_16x16x32_bf16 v[66:69], v[168:171], v[214:217], v[66:69]
	v_mfma_f32_16x16x32_bf16 v[66:69], v[186:189], v[218:221], v[66:69]
	v_mfma_f32_16x16x32_bf16 v[82:85], v[186:189], v[210:213], v[82:85]
	v_mfma_f32_16x16x32_bf16 v[82:85], v[168:171], v[206:209], v[82:85]
	v_mfma_f32_16x16x32_bf16 v[98:101], v[168:171], v[198:201], v[98:101]
	v_mfma_f32_16x16x32_bf16 v[98:101], v[186:189], v[202:205], v[98:101]
	v_mfma_f32_16x16x32_bf16 v[114:117], v[186:189], v[194:197], v[114:117]
	v_mfma_f32_16x16x32_bf16 v[114:117], v[168:171], v[190:193], v[114:117]
	s_barrier
	s_add_i32 s30, s62, s49
	v_lshl_add_u64 v[172:173], v[172:173], 0, s[98:99]
	s_mov_b32 m0, s30
	ds_read_b128 v[190:193], v184 offset:49152
	ds_read_b128 v[194:197], v184 offset:50176
	ds_read_b128 v[198:201], v184 offset:51200
	ds_read_b128 v[202:205], v184 offset:52224
	ds_read_b128 v[206:209], v184 offset:53248
	ds_read_b128 v[210:213], v184 offset:54272
	ds_read_b128 v[214:217], v184 offset:55296
	ds_read_b128 v[218:221], v184 offset:56320
	global_load_lds_dwordx4 v[172:173], off
	v_lshl_add_u64 v[172:173], v[222:223], 0, s[98:99]
	s_add_i32 m0, s30, 0x2000
	s_add_i32 s30, s63, s49
	global_load_lds_dwordx4 v[172:173], off
	v_lshl_add_u64 v[172:173], v[236:237], 0, s[98:99]
	s_mov_b32 m0, s30
	s_nop 0
	global_load_lds_dwordx4 v[172:173], off
	v_lshl_add_u64 v[172:173], v[238:239], 0, s[98:99]
	s_add_i32 m0, s30, 0x2000
	s_nop 0
	global_load_lds_dwordx4 v[172:173], off
	v_lshl_add_u64 v[172:173], v[240:241], 0, s[98:99]
	s_mov_b32 m0, s95
	s_nop 0
	global_load_lds_dwordx4 v[172:173], off
	v_lshl_add_u64 v[172:173], v[242:243], 0, s[98:99]
	s_mov_b32 m0, s54
	s_nop 0
	global_load_lds_dwordx4 v[172:173], off
	s_waitcnt vmcnt(8)
	s_waitcnt lgkmcnt(0)
	s_barrier
	s_waitcnt lgkmcnt(0)
	v_mfma_f32_16x16x32_bf16 v[62:65], v[130:133], v[190:193], v[62:65]
	v_mfma_f32_16x16x32_bf16 v[62:65], v[134:137], v[194:197], v[62:65]
	v_mfma_f32_16x16x32_bf16 v[46:49], v[134:137], v[202:205], v[46:49]
	v_mfma_f32_16x16x32_bf16 v[46:49], v[130:133], v[198:201], v[46:49]
	v_mfma_f32_16x16x32_bf16 v[30:33], v[130:133], v[206:209], v[30:33]
	v_mfma_f32_16x16x32_bf16 v[30:33], v[134:137], v[210:213], v[30:33]
	v_mfma_f32_16x16x32_bf16 v[14:17], v[134:137], v[218:221], v[14:17]
	v_mfma_f32_16x16x32_bf16 v[14:17], v[130:133], v[214:217], v[14:17]
	v_mfma_f32_16x16x32_bf16 v[10:13], v[152:155], v[214:217], v[10:13]
	v_mfma_f32_16x16x32_bf16 v[10:13], v[156:159], v[218:221], v[10:13]
	v_mfma_f32_16x16x32_bf16 v[26:29], v[156:159], v[210:213], v[26:29]
	v_mfma_f32_16x16x32_bf16 v[26:29], v[152:155], v[206:209], v[26:29]
	v_mfma_f32_16x16x32_bf16 v[42:45], v[152:155], v[198:201], v[42:45]
	v_mfma_f32_16x16x32_bf16 v[42:45], v[156:159], v[202:205], v[42:45]
	v_mfma_f32_16x16x32_bf16 v[58:61], v[156:159], v[194:197], v[58:61]
	v_mfma_f32_16x16x32_bf16 v[58:61], v[152:155], v[190:193], v[58:61]
	v_mfma_f32_16x16x32_bf16 v[54:57], v[160:163], v[190:193], v[54:57]
	v_mfma_f32_16x16x32_bf16 v[54:57], v[164:167], v[194:197], v[54:57]
	v_mfma_f32_16x16x32_bf16 v[38:41], v[164:167], v[202:205], v[38:41]
	v_mfma_f32_16x16x32_bf16 v[38:41], v[160:163], v[198:201], v[38:41]
	v_mfma_f32_16x16x32_bf16 v[22:25], v[160:163], v[206:209], v[22:25]
	v_mfma_f32_16x16x32_bf16 v[22:25], v[164:167], v[210:213], v[22:25]
	v_mfma_f32_16x16x32_bf16 v[6:9], v[164:167], v[218:221], v[6:9]
	v_mfma_f32_16x16x32_bf16 v[6:9], v[160:163], v[214:217], v[6:9]
	v_mfma_f32_16x16x32_bf16 v[2:5], v[168:171], v[214:217], v[2:5]
	v_mfma_f32_16x16x32_bf16 v[2:5], v[186:189], v[218:221], v[2:5]
	v_mfma_f32_16x16x32_bf16 v[18:21], v[186:189], v[210:213], v[18:21]
	v_mfma_f32_16x16x32_bf16 v[18:21], v[168:171], v[206:209], v[18:21]
	v_mfma_f32_16x16x32_bf16 v[34:37], v[168:171], v[198:201], v[34:37]
	v_mfma_f32_16x16x32_bf16 v[34:37], v[186:189], v[202:205], v[34:37]
	v_mfma_f32_16x16x32_bf16 v[50:53], v[186:189], v[194:197], v[50:53]
	v_mfma_f32_16x16x32_bf16 v[50:53], v[168:171], v[190:193], v[50:53]
	s_barrier
	s_add_u32 s28, s28, 0x100
	s_addc_u32 s29, s29, 0
	s_add_u32 s23, s23, 0x100
	s_addc_u32 s40, s40, 0
	s_cmp_ge_i32 s41, s61
	s_mov_b32 s30, s41
	s_cbranch_scc1 .Lpeel_done_217
.LBB0_217:
	s_add_i32 s41, s30, 2
	s_add_u32 vcc_lo, s28, 0x80
	s_addc_u32 s31, s29, 0
	s_add_i32 s62, 0, 0x10000
	s_cmp_eq_u32 s13, s30
	s_cselect_b32 s31, s25, s31
	s_cselect_b32 s30, s24, vcc_lo
	v_add_u32_e32 v145, s62, v175
	s_cselect_b32 vcc_hi, s27, s40
	s_cselect_b32 vcc_lo, s26, s23
	s_add_i32 s63, 0, 0x14000
	ds_read_b128 v[130:133], v145
	ds_read_b128 v[134:137], v145 offset:1024
	ds_read_b128 v[152:155], v145 offset:2048
	ds_read_b128 v[156:159], v145 offset:3072
	v_add_u32_e32 v145, s63, v175
	ds_read_b128 v[160:163], v145
	ds_read_b128 v[164:167], v145 offset:1024
	ds_read_b128 v[168:171], v145 offset:2048
	ds_read_b128 v[186:189], v145 offset:3072
	v_lshl_add_u64 v[172:173], s[28:29], 0, v[148:149]
	s_add_i32 m0, s93, 0xc000
	ds_read_b128 v[190:193], v184
	ds_read_b128 v[194:197], v184 offset:1024
	ds_read_b128 v[198:201], v184 offset:2048
	ds_read_b128 v[202:205], v184 offset:3072
	ds_read_b128 v[206:209], v184 offset:4096
	ds_read_b128 v[210:213], v184 offset:5120
	ds_read_b128 v[214:217], v184 offset:6144
	ds_read_b128 v[218:221], v184 offset:7168
	global_load_lds_dwordx4 v[172:173], off
	v_lshl_add_u64 v[172:173], s[28:29], 0, v[150:151]
	s_add_i32 m0, s93, 0xe000
	s_nop 0
	global_load_lds_dwordx4 v[172:173], off
	s_waitcnt vmcnt(8)
	s_waitcnt lgkmcnt(0)
	s_barrier
	s_waitcnt lgkmcnt(0)
	v_mfma_f32_16x16x32_bf16 v[126:129], v[130:133], v[190:193], v[126:129]
	v_mfma_f32_16x16x32_bf16 v[126:129], v[134:137], v[194:197], v[126:129]
	v_mfma_f32_16x16x32_bf16 v[110:113], v[134:137], v[202:205], v[110:113]
	v_mfma_f32_16x16x32_bf16 v[110:113], v[130:133], v[198:201], v[110:113]
	v_mfma_f32_16x16x32_bf16 v[94:97], v[130:133], v[206:209], v[94:97]
	v_mfma_f32_16x16x32_bf16 v[94:97], v[134:137], v[210:213], v[94:97]
	v_mfma_f32_16x16x32_bf16 v[78:81], v[134:137], v[218:221], v[78:81]
	v_mfma_f32_16x16x32_bf16 v[78:81], v[130:133], v[214:217], v[78:81]
	v_mfma_f32_16x16x32_bf16 v[74:77], v[152:155], v[214:217], v[74:77]
	v_mfma_f32_16x16x32_bf16 v[74:77], v[156:159], v[218:221], v[74:77]
	v_mfma_f32_16x16x32_bf16 v[90:93], v[156:159], v[210:213], v[90:93]
	v_mfma_f32_16x16x32_bf16 v[90:93], v[152:155], v[206:209], v[90:93]
	v_mfma_f32_16x16x32_bf16 v[106:109], v[152:155], v[198:201], v[106:109]
	v_mfma_f32_16x16x32_bf16 v[106:109], v[156:159], v[202:205], v[106:109]
	v_mfma_f32_16x16x32_bf16 v[122:125], v[156:159], v[194:197], v[122:125]
	v_mfma_f32_16x16x32_bf16 v[122:125], v[152:155], v[190:193], v[122:125]
	v_mfma_f32_16x16x32_bf16 v[118:121], v[160:163], v[190:193], v[118:121]
	v_mfma_f32_16x16x32_bf16 v[118:121], v[164:167], v[194:197], v[118:121]
	v_mfma_f32_16x16x32_bf16 v[102:105], v[164:167], v[202:205], v[102:105]
	v_mfma_f32_16x16x32_bf16 v[102:105], v[160:163], v[198:201], v[102:105]
	v_mfma_f32_16x16x32_bf16 v[86:89], v[160:163], v[206:209], v[86:89]
	v_mfma_f32_16x16x32_bf16 v[86:89], v[164:167], v[210:213], v[86:89]
	v_mfma_f32_16x16x32_bf16 v[70:73], v[164:167], v[218:221], v[70:73]
	v_mfma_f32_16x16x32_bf16 v[70:73], v[160:163], v[214:217], v[70:73]
	v_mfma_f32_16x16x32_bf16 v[66:69], v[168:171], v[214:217], v[66:69]
	v_mfma_f32_16x16x32_bf16 v[66:69], v[186:189], v[218:221], v[66:69]
	v_mfma_f32_16x16x32_bf16 v[82:85], v[186:189], v[210:213], v[82:85]
	v_mfma_f32_16x16x32_bf16 v[82:85], v[168:171], v[206:209], v[82:85]
	v_mfma_f32_16x16x32_bf16 v[98:101], v[168:171], v[198:201], v[98:101]
	v_mfma_f32_16x16x32_bf16 v[98:101], v[186:189], v[202:205], v[98:101]
	v_mfma_f32_16x16x32_bf16 v[114:117], v[186:189], v[194:197], v[114:117]
	v_mfma_f32_16x16x32_bf16 v[114:117], v[168:171], v[190:193], v[114:117]
	s_barrier
	s_add_i32 s62, s62, s49
	v_lshl_add_u64 v[172:173], vcc, 0, v[0:1]
	s_mov_b32 m0, s62
	ds_read_b128 v[190:193], v184 offset:16384
	ds_read_b128 v[194:197], v184 offset:17408
	ds_read_b128 v[198:201], v184 offset:18432
	ds_read_b128 v[202:205], v184 offset:19456
	ds_read_b128 v[206:209], v184 offset:20480
	ds_read_b128 v[210:213], v184 offset:21504
	ds_read_b128 v[214:217], v184 offset:22528
	ds_read_b128 v[218:221], v184 offset:23552
	global_load_lds_dwordx4 v[172:173], off
	s_add_i32 m0, s62, 0x2000
	v_lshl_add_u64 v[222:223], vcc, 0, v[142:143]
	s_add_u32 vcc_lo, vcc_lo, s96
	s_addc_u32 vcc_hi, vcc_hi, 0
	s_add_i32 s62, s63, s49
	global_load_lds_dwordx4 v[222:223], off
	v_lshl_add_u64 v[236:237], vcc, 0, v[0:1]
	s_mov_b32 m0, s62
	v_lshl_add_u64 v[238:239], vcc, 0, v[142:143]
	global_load_lds_dwordx4 v[236:237], off
	s_add_i32 m0, s62, 0x2000
	v_lshl_add_u64 v[240:241], s[30:31], 0, v[138:139]
	global_load_lds_dwordx4 v[238:239], off
	s_mov_b32 m0, s93
	v_lshl_add_u64 v[242:243], s[30:31], 0, v[140:141]
	global_load_lds_dwordx4 v[240:241], off
	s_mov_b32 m0, s88
	s_nop 0
	global_load_lds_dwordx4 v[242:243], off
	s_waitcnt vmcnt(8)
	s_waitcnt lgkmcnt(0)
	s_barrier
	s_waitcnt lgkmcnt(0)
	v_mfma_f32_16x16x32_bf16 v[62:65], v[130:133], v[190:193], v[62:65]
	v_mfma_f32_16x16x32_bf16 v[62:65], v[134:137], v[194:197], v[62:65]
	v_mfma_f32_16x16x32_bf16 v[46:49], v[134:137], v[202:205], v[46:49]
	v_mfma_f32_16x16x32_bf16 v[46:49], v[130:133], v[198:201], v[46:49]
	v_mfma_f32_16x16x32_bf16 v[30:33], v[130:133], v[206:209], v[30:33]
	v_mfma_f32_16x16x32_bf16 v[30:33], v[134:137], v[210:213], v[30:33]
	v_mfma_f32_16x16x32_bf16 v[14:17], v[134:137], v[218:221], v[14:17]
	v_mfma_f32_16x16x32_bf16 v[14:17], v[130:133], v[214:217], v[14:17]
	v_mfma_f32_16x16x32_bf16 v[10:13], v[152:155], v[214:217], v[10:13]
	v_mfma_f32_16x16x32_bf16 v[10:13], v[156:159], v[218:221], v[10:13]
	v_mfma_f32_16x16x32_bf16 v[26:29], v[156:159], v[210:213], v[26:29]
	v_mfma_f32_16x16x32_bf16 v[26:29], v[152:155], v[206:209], v[26:29]
	v_mfma_f32_16x16x32_bf16 v[42:45], v[152:155], v[198:201], v[42:45]
	v_mfma_f32_16x16x32_bf16 v[42:45], v[156:159], v[202:205], v[42:45]
	v_mfma_f32_16x16x32_bf16 v[58:61], v[156:159], v[194:197], v[58:61]
	v_mfma_f32_16x16x32_bf16 v[58:61], v[152:155], v[190:193], v[58:61]
	v_mfma_f32_16x16x32_bf16 v[54:57], v[160:163], v[190:193], v[54:57]
	v_mfma_f32_16x16x32_bf16 v[54:57], v[164:167], v[194:197], v[54:57]
	v_mfma_f32_16x16x32_bf16 v[38:41], v[164:167], v[202:205], v[38:41]
	v_mfma_f32_16x16x32_bf16 v[38:41], v[160:163], v[198:201], v[38:41]
	v_mfma_f32_16x16x32_bf16 v[22:25], v[160:163], v[206:209], v[22:25]
	v_mfma_f32_16x16x32_bf16 v[22:25], v[164:167], v[210:213], v[22:25]
	v_mfma_f32_16x16x32_bf16 v[6:9], v[164:167], v[218:221], v[6:9]
	v_mfma_f32_16x16x32_bf16 v[6:9], v[160:163], v[214:217], v[6:9]
	v_mfma_f32_16x16x32_bf16 v[2:5], v[168:171], v[214:217], v[2:5]
	v_mfma_f32_16x16x32_bf16 v[2:5], v[186:189], v[218:221], v[2:5]
	v_mfma_f32_16x16x32_bf16 v[18:21], v[186:189], v[210:213], v[18:21]
	v_mfma_f32_16x16x32_bf16 v[18:21], v[168:171], v[206:209], v[18:21]
	v_mfma_f32_16x16x32_bf16 v[34:37], v[168:171], v[198:201], v[34:37]
	v_mfma_f32_16x16x32_bf16 v[34:37], v[186:189], v[202:205], v[34:37]
	v_mfma_f32_16x16x32_bf16 v[50:53], v[186:189], v[194:197], v[50:53]
	v_mfma_f32_16x16x32_bf16 v[50:53], v[168:171], v[190:193], v[50:53]
	s_barrier
	s_add_i32 s62, 0, 0x18000
	v_add_u32_e32 v145, s62, v175
	s_add_i32 s63, 0, 0x1c000
	ds_read_b128 v[130:133], v145
	ds_read_b128 v[134:137], v145 offset:1024
	ds_read_b128 v[152:155], v145 offset:2048
	ds_read_b128 v[156:159], v145 offset:3072
	v_add_u32_e32 v145, s63, v175
	ds_read_b128 v[160:163], v145
	ds_read_b128 v[164:167], v145 offset:1024
	ds_read_b128 v[168:171], v145 offset:2048
	ds_read_b128 v[186:189], v145 offset:3072
	s_add_u32 s30, s30, s96
	s_addc_u32 s31, s31, 0
	s_mov_b32 m0, s89
	v_lshl_add_u64 v[244:245], s[30:31], 0, v[138:139]
	ds_read_b128 v[190:193], v184 offset:32768
	ds_read_b128 v[194:197], v184 offset:33792
	ds_read_b128 v[198:201], v184 offset:34816
	ds_read_b128 v[202:205], v184 offset:35840
	ds_read_b128 v[206:209], v184 offset:36864
	ds_read_b128 v[210:213], v184 offset:37888
	ds_read_b128 v[214:217], v184 offset:38912
	ds_read_b128 v[218:221], v184 offset:39936
	global_load_lds_dwordx4 v[244:245], off
	v_lshl_add_u64 v[244:245], s[30:31], 0, v[140:141]
	s_mov_b32 m0, s52
	s_nop 0
	global_load_lds_dwordx4 v[244:245], off
	s_waitcnt vmcnt(8)
	s_waitcnt lgkmcnt(0)
	s_barrier
	s_waitcnt lgkmcnt(0)
	v_mfma_f32_16x16x32_bf16 v[126:129], v[130:133], v[190:193], v[126:129]
	v_mfma_f32_16x16x32_bf16 v[126:129], v[134:137], v[194:197], v[126:129]
	v_mfma_f32_16x16x32_bf16 v[110:113], v[134:137], v[202:205], v[110:113]
	v_mfma_f32_16x16x32_bf16 v[110:113], v[130:133], v[198:201], v[110:113]
	v_mfma_f32_16x16x32_bf16 v[94:97], v[130:133], v[206:209], v[94:97]
	v_mfma_f32_16x16x32_bf16 v[94:97], v[134:137], v[210:213], v[94:97]
	v_mfma_f32_16x16x32_bf16 v[78:81], v[134:137], v[218:221], v[78:81]
	v_mfma_f32_16x16x32_bf16 v[78:81], v[130:133], v[214:217], v[78:81]
	v_mfma_f32_16x16x32_bf16 v[74:77], v[152:155], v[214:217], v[74:77]
	v_mfma_f32_16x16x32_bf16 v[74:77], v[156:159], v[218:221], v[74:77]
	v_mfma_f32_16x16x32_bf16 v[90:93], v[156:159], v[210:213], v[90:93]
	v_mfma_f32_16x16x32_bf16 v[90:93], v[152:155], v[206:209], v[90:93]
	v_mfma_f32_16x16x32_bf16 v[106:109], v[152:155], v[198:201], v[106:109]
	v_mfma_f32_16x16x32_bf16 v[106:109], v[156:159], v[202:205], v[106:109]
	v_mfma_f32_16x16x32_bf16 v[122:125], v[156:159], v[194:197], v[122:125]
	v_mfma_f32_16x16x32_bf16 v[122:125], v[152:155], v[190:193], v[122:125]
	v_mfma_f32_16x16x32_bf16 v[118:121], v[160:163], v[190:193], v[118:121]
	v_mfma_f32_16x16x32_bf16 v[118:121], v[164:167], v[194:197], v[118:121]
	v_mfma_f32_16x16x32_bf16 v[102:105], v[164:167], v[202:205], v[102:105]
	v_mfma_f32_16x16x32_bf16 v[102:105], v[160:163], v[198:201], v[102:105]
	v_mfma_f32_16x16x32_bf16 v[86:89], v[160:163], v[206:209], v[86:89]
	v_mfma_f32_16x16x32_bf16 v[86:89], v[164:167], v[210:213], v[86:89]
	v_mfma_f32_16x16x32_bf16 v[70:73], v[164:167], v[218:221], v[70:73]
	v_mfma_f32_16x16x32_bf16 v[70:73], v[160:163], v[214:217], v[70:73]
	v_mfma_f32_16x16x32_bf16 v[66:69], v[168:171], v[214:217], v[66:69]
	v_mfma_f32_16x16x32_bf16 v[66:69], v[186:189], v[218:221], v[66:69]
	v_mfma_f32_16x16x32_bf16 v[82:85], v[186:189], v[210:213], v[82:85]
	v_mfma_f32_16x16x32_bf16 v[82:85], v[168:171], v[206:209], v[82:85]
	v_mfma_f32_16x16x32_bf16 v[98:101], v[168:171], v[198:201], v[98:101]
	v_mfma_f32_16x16x32_bf16 v[98:101], v[186:189], v[202:205], v[98:101]
	v_mfma_f32_16x16x32_bf16 v[114:117], v[186:189], v[194:197], v[114:117]
	v_mfma_f32_16x16x32_bf16 v[114:117], v[168:171], v[190:193], v[114:117]
	s_barrier
	s_add_i32 s30, s62, s49
	v_lshl_add_u64 v[172:173], v[172:173], 0, s[98:99]
	s_mov_b32 m0, s30
	ds_read_b128 v[190:193], v184 offset:49152
	ds_read_b128 v[194:197], v184 offset:50176
	ds_read_b128 v[198:201], v184 offset:51200
	ds_read_b128 v[202:205], v184 offset:52224
	ds_read_b128 v[206:209], v184 offset:53248
	ds_read_b128 v[210:213], v184 offset:54272
	ds_read_b128 v[214:217], v184 offset:55296
	ds_read_b128 v[218:221], v184 offset:56320
	global_load_lds_dwordx4 v[172:173], off
	v_lshl_add_u64 v[172:173], v[222:223], 0, s[98:99]
	s_add_i32 m0, s30, 0x2000
	s_add_i32 s30, s63, s49
	global_load_lds_dwordx4 v[172:173], off
	v_lshl_add_u64 v[172:173], v[236:237], 0, s[98:99]
	s_mov_b32 m0, s30
	s_nop 0
	global_load_lds_dwordx4 v[172:173], off
	v_lshl_add_u64 v[172:173], v[238:239], 0, s[98:99]
	s_add_i32 m0, s30, 0x2000
	s_nop 0
	global_load_lds_dwordx4 v[172:173], off
	v_lshl_add_u64 v[172:173], v[240:241], 0, s[98:99]
	s_mov_b32 m0, s95
	s_nop 0
	global_load_lds_dwordx4 v[172:173], off
	v_lshl_add_u64 v[172:173], v[242:243], 0, s[98:99]
	s_mov_b32 m0, s54
	s_nop 0
	global_load_lds_dwordx4 v[172:173], off
	s_waitcnt vmcnt(8)
	s_waitcnt lgkmcnt(0)
	s_barrier
	s_waitcnt lgkmcnt(0)
	v_mfma_f32_16x16x32_bf16 v[62:65], v[130:133], v[190:193], v[62:65]
	v_mfma_f32_16x16x32_bf16 v[62:65], v[134:137], v[194:197], v[62:65]
	v_mfma_f32_16x16x32_bf16 v[46:49], v[134:137], v[202:205], v[46:49]
	v_mfma_f32_16x16x32_bf16 v[46:49], v[130:133], v[198:201], v[46:49]
	v_mfma_f32_16x16x32_bf16 v[30:33], v[130:133], v[206:209], v[30:33]
	v_mfma_f32_16x16x32_bf16 v[30:33], v[134:137], v[210:213], v[30:33]
	v_mfma_f32_16x16x32_bf16 v[14:17], v[134:137], v[218:221], v[14:17]
	v_mfma_f32_16x16x32_bf16 v[14:17], v[130:133], v[214:217], v[14:17]
	v_mfma_f32_16x16x32_bf16 v[10:13], v[152:155], v[214:217], v[10:13]
	v_mfma_f32_16x16x32_bf16 v[10:13], v[156:159], v[218:221], v[10:13]
	v_mfma_f32_16x16x32_bf16 v[26:29], v[156:159], v[210:213], v[26:29]
	v_mfma_f32_16x16x32_bf16 v[26:29], v[152:155], v[206:209], v[26:29]
	v_mfma_f32_16x16x32_bf16 v[42:45], v[152:155], v[198:201], v[42:45]
	v_mfma_f32_16x16x32_bf16 v[42:45], v[156:159], v[202:205], v[42:45]
	v_mfma_f32_16x16x32_bf16 v[58:61], v[156:159], v[194:197], v[58:61]
	v_mfma_f32_16x16x32_bf16 v[58:61], v[152:155], v[190:193], v[58:61]
	v_mfma_f32_16x16x32_bf16 v[54:57], v[160:163], v[190:193], v[54:57]
	v_mfma_f32_16x16x32_bf16 v[54:57], v[164:167], v[194:197], v[54:57]
	v_mfma_f32_16x16x32_bf16 v[38:41], v[164:167], v[202:205], v[38:41]
	v_mfma_f32_16x16x32_bf16 v[38:41], v[160:163], v[198:201], v[38:41]
	v_mfma_f32_16x16x32_bf16 v[22:25], v[160:163], v[206:209], v[22:25]
	v_mfma_f32_16x16x32_bf16 v[22:25], v[164:167], v[210:213], v[22:25]
	v_mfma_f32_16x16x32_bf16 v[6:9], v[164:167], v[218:221], v[6:9]
	v_mfma_f32_16x16x32_bf16 v[6:9], v[160:163], v[214:217], v[6:9]
	v_mfma_f32_16x16x32_bf16 v[2:5], v[168:171], v[214:217], v[2:5]
	v_mfma_f32_16x16x32_bf16 v[2:5], v[186:189], v[218:221], v[2:5]
	v_mfma_f32_16x16x32_bf16 v[18:21], v[186:189], v[210:213], v[18:21]
	v_mfma_f32_16x16x32_bf16 v[18:21], v[168:171], v[206:209], v[18:21]
	v_mfma_f32_16x16x32_bf16 v[34:37], v[168:171], v[198:201], v[34:37]
	v_mfma_f32_16x16x32_bf16 v[34:37], v[186:189], v[202:205], v[34:37]
	v_mfma_f32_16x16x32_bf16 v[50:53], v[186:189], v[194:197], v[50:53]
	v_mfma_f32_16x16x32_bf16 v[50:53], v[168:171], v[190:193], v[50:53]
	s_barrier
	s_add_u32 s28, s28, 0x100
	s_addc_u32 s29, s29, 0
	s_add_u32 s23, s23, 0x100
	s_addc_u32 s40, s40, 0
	s_cmp_ge_i32 s41, s61
	s_mov_b32 s30, s41
	s_cbranch_scc0 .LBB0_217

.LBB0_373:
	s_ashr_i32 s17, s16, 31
	s_lshl_b64 s[20:21], s[16:17], 19
	s_add_u32 s20, s37, s20
	s_addc_u32 s21, s40, s21
	s_and_b64 s[22:23], s[18:19], exec
	s_cselect_b32 s17, s21, s29
	s_cselect_b32 s25, s20, s28
	s_ashr_i32 s15, s14, 31
	s_lshl_b64 s[22:23], s[14:15], 19
	s_add_u32 s22, s41, s22
	s_addc_u32 s23, s42, s23
	s_and_b64 s[38:39], s[18:19], exec
	s_cselect_b32 s15, s23, s31
	s_cselect_b32 s53, s22, s30
	s_add_u32 s28, s28, 0x40080
	s_addc_u32 s29, s29, 0
	s_add_u32 s54, s30, 0x100
	s_addc_u32 s55, s31, 0
	s_mov_b32 s56, -2
	s_add_u32 s30, s28, 0xfffc0080
	s_addc_u32 s31, s29, -1
	s_add_i32 s57, 0, 0x10000
	s_cmp_eq_u32 s56, 12
	s_cselect_b32 s39, s17, s31
	s_cselect_b32 s38, s25, s30
	s_cselect_b32 s31, s15, s55
	s_cselect_b32 s30, s53, s54
	s_add_i32 s60, 0, 0x14000
	v_add_u32_e32 v156, s57, v145
	v_add_u32_e32 v172, s60, v145
	ds_read_b128 v[140:143], v156
	ds_read_b128 v[148:151], v156 offset:1024
	ds_read_b128 v[152:155], v156 offset:2048
	ds_read_b128 v[156:159], v156 offset:3072
	ds_read_b128 v[160:163], v172
	ds_read_b128 v[164:167], v172 offset:1024
	ds_read_b128 v[168:171], v172 offset:2048
	ds_read_b128 v[172:175], v172 offset:3072
	v_lshl_add_u64 v[208:209], s[28:29], 0, v[136:137]
	s_add_i32 m0, s27, 0xc000
	ds_read_b128 v[176:179], v147
	ds_read_b128 v[180:183], v147 offset:1024
	ds_read_b128 v[184:187], v147 offset:2048
	ds_read_b128 v[188:191], v147 offset:3072
	ds_read_b128 v[192:195], v147 offset:4096
	ds_read_b128 v[196:199], v147 offset:5120
	ds_read_b128 v[200:203], v147 offset:6144
	ds_read_b128 v[204:207], v147 offset:7168
	global_load_lds_dwordx4 v[208:209], off
	v_lshl_add_u64 v[208:209], s[28:29], 0, v[138:139]
	s_add_i32 m0, s27, 0xe000
	s_nop 0
	global_load_lds_dwordx4 v[208:209], off
	s_waitcnt vmcnt(8)
	s_waitcnt lgkmcnt(0)
	s_barrier
	s_waitcnt lgkmcnt(0)
	v_mfma_f32_16x16x32_bf16 v[122:125], v[140:143], v[176:179], 0
	v_mfma_f32_16x16x32_bf16 v[122:125], v[148:151], v[180:183], v[122:125]
	v_mfma_f32_16x16x32_bf16 v[106:109], v[148:151], v[188:191], 0
	v_mfma_f32_16x16x32_bf16 v[106:109], v[140:143], v[184:187], v[106:109]
	v_mfma_f32_16x16x32_bf16 v[90:93], v[140:143], v[192:195], 0
	v_mfma_f32_16x16x32_bf16 v[90:93], v[148:151], v[196:199], v[90:93]
	v_mfma_f32_16x16x32_bf16 v[74:77], v[148:151], v[204:207], 0
	v_mfma_f32_16x16x32_bf16 v[74:77], v[140:143], v[200:203], v[74:77]
	v_mfma_f32_16x16x32_bf16 v[66:69], v[152:155], v[200:203], 0
	v_mfma_f32_16x16x32_bf16 v[66:69], v[156:159], v[204:207], v[66:69]
	v_mfma_f32_16x16x32_bf16 v[82:85], v[156:159], v[196:199], 0
	v_mfma_f32_16x16x32_bf16 v[82:85], v[152:155], v[192:195], v[82:85]
	v_mfma_f32_16x16x32_bf16 v[98:101], v[152:155], v[184:187], 0
	v_mfma_f32_16x16x32_bf16 v[98:101], v[156:159], v[188:191], v[98:101]
	v_mfma_f32_16x16x32_bf16 v[114:117], v[156:159], v[180:183], 0
	v_mfma_f32_16x16x32_bf16 v[114:117], v[152:155], v[176:179], v[114:117]
	v_mfma_f32_16x16x32_bf16 v[126:129], v[160:163], v[176:179], 0
	v_mfma_f32_16x16x32_bf16 v[126:129], v[164:167], v[180:183], v[126:129]
	v_mfma_f32_16x16x32_bf16 v[110:113], v[164:167], v[188:191], 0
	v_mfma_f32_16x16x32_bf16 v[110:113], v[160:163], v[184:187], v[110:113]
	v_mfma_f32_16x16x32_bf16 v[94:97], v[160:163], v[192:195], 0
	v_mfma_f32_16x16x32_bf16 v[94:97], v[164:167], v[196:199], v[94:97]
	v_mfma_f32_16x16x32_bf16 v[78:81], v[164:167], v[204:207], 0
	v_mfma_f32_16x16x32_bf16 v[78:81], v[160:163], v[200:203], v[78:81]
	v_mfma_f32_16x16x32_bf16 v[70:73], v[168:171], v[200:203], 0
	v_mfma_f32_16x16x32_bf16 v[70:73], v[172:175], v[204:207], v[70:73]
	v_mfma_f32_16x16x32_bf16 v[86:89], v[172:175], v[196:199], 0
	v_mfma_f32_16x16x32_bf16 v[86:89], v[168:171], v[192:195], v[86:89]
	v_mfma_f32_16x16x32_bf16 v[102:105], v[168:171], v[184:187], 0
	v_mfma_f32_16x16x32_bf16 v[102:105], v[172:175], v[188:191], v[102:105]
	v_mfma_f32_16x16x32_bf16 v[118:121], v[172:175], v[180:183], 0
	v_mfma_f32_16x16x32_bf16 v[118:121], v[168:171], v[176:179], v[118:121]
	s_barrier
	s_add_i32 s57, s57, s43
	v_lshl_add_u64 v[208:209], s[30:31], 0, v[0:1]
	s_mov_b32 m0, s57
	ds_read_b128 v[176:179], v147 offset:16384
	ds_read_b128 v[180:183], v147 offset:17408
	ds_read_b128 v[184:187], v147 offset:18432
	ds_read_b128 v[188:191], v147 offset:19456
	ds_read_b128 v[192:195], v147 offset:20480
	ds_read_b128 v[196:199], v147 offset:21504
	ds_read_b128 v[200:203], v147 offset:22528
	ds_read_b128 v[204:207], v147 offset:23552
	global_load_lds_dwordx4 v[208:209], off
	s_add_i32 m0, s57, 0x2000
	s_add_u32 s58, s30, 0x40000
	v_lshl_add_u64 v[210:211], s[30:31], 0, v[134:135]
	s_addc_u32 s59, s31, 0
	s_add_i32 s57, s60, s43
	global_load_lds_dwordx4 v[210:211], off
	v_lshl_add_u64 v[212:213], s[58:59], 0, v[0:1]
	s_mov_b32 m0, s57
	v_lshl_add_u64 v[214:215], s[38:39], 0, v[132:133]
	global_load_lds_dwordx4 v[212:213], off
	v_lshl_add_u64 v[212:213], s[58:59], 0, v[134:135]
	s_add_i32 m0, s57, 0x2000
	s_nop 0
	global_load_lds_dwordx4 v[212:213], off
	v_lshl_add_u64 v[212:213], s[38:39], 0, v[130:131]
	s_mov_b32 m0, s27
	s_nop 0
	global_load_lds_dwordx4 v[212:213], off
	s_mov_b32 m0, s44
	s_nop 0
	global_load_lds_dwordx4 v[214:215], off
	s_waitcnt vmcnt(8)
	s_waitcnt lgkmcnt(0)
	s_barrier
	s_waitcnt lgkmcnt(0)
	v_mfma_f32_16x16x32_bf16 v[58:61], v[140:143], v[176:179], 0
	v_mfma_f32_16x16x32_bf16 v[58:61], v[148:151], v[180:183], v[58:61]
	v_mfma_f32_16x16x32_bf16 v[42:45], v[148:151], v[188:191], 0
	v_mfma_f32_16x16x32_bf16 v[42:45], v[140:143], v[184:187], v[42:45]
	v_mfma_f32_16x16x32_bf16 v[26:29], v[140:143], v[192:195], 0
	v_mfma_f32_16x16x32_bf16 v[26:29], v[148:151], v[196:199], v[26:29]
	v_mfma_f32_16x16x32_bf16 v[10:13], v[148:151], v[204:207], 0
	v_mfma_f32_16x16x32_bf16 v[10:13], v[140:143], v[200:203], v[10:13]
	v_mfma_f32_16x16x32_bf16 v[6:9], v[152:155], v[200:203], 0
	v_mfma_f32_16x16x32_bf16 v[6:9], v[156:159], v[204:207], v[6:9]
	v_mfma_f32_16x16x32_bf16 v[18:21], v[156:159], v[196:199], 0
	v_mfma_f32_16x16x32_bf16 v[18:21], v[152:155], v[192:195], v[18:21]
	v_mfma_f32_16x16x32_bf16 v[34:37], v[152:155], v[184:187], 0
	v_mfma_f32_16x16x32_bf16 v[34:37], v[156:159], v[188:191], v[34:37]
	v_mfma_f32_16x16x32_bf16 v[50:53], v[156:159], v[180:183], 0
	v_mfma_f32_16x16x32_bf16 v[50:53], v[152:155], v[176:179], v[50:53]
	v_mfma_f32_16x16x32_bf16 v[62:65], v[160:163], v[176:179], 0
	v_mfma_f32_16x16x32_bf16 v[62:65], v[164:167], v[180:183], v[62:65]
	v_mfma_f32_16x16x32_bf16 v[46:49], v[164:167], v[188:191], 0
	v_mfma_f32_16x16x32_bf16 v[46:49], v[160:163], v[184:187], v[46:49]
	v_mfma_f32_16x16x32_bf16 v[30:33], v[160:163], v[192:195], 0
	v_mfma_f32_16x16x32_bf16 v[30:33], v[164:167], v[196:199], v[30:33]
	v_mfma_f32_16x16x32_bf16 v[14:17], v[164:167], v[204:207], 0
	v_mfma_f32_16x16x32_bf16 v[14:17], v[160:163], v[200:203], v[14:17]
	v_mfma_f32_16x16x32_bf16 v[2:5], v[168:171], v[200:203], 0
	v_mfma_f32_16x16x32_bf16 v[2:5], v[172:175], v[204:207], v[2:5]
	v_mfma_f32_16x16x32_bf16 v[22:25], v[172:175], v[196:199], 0
	v_mfma_f32_16x16x32_bf16 v[22:25], v[168:171], v[192:195], v[22:25]
	v_mfma_f32_16x16x32_bf16 v[38:41], v[168:171], v[184:187], 0
	v_mfma_f32_16x16x32_bf16 v[38:41], v[172:175], v[188:191], v[38:41]
	v_mfma_f32_16x16x32_bf16 v[54:57], v[172:175], v[180:183], 0
	v_mfma_f32_16x16x32_bf16 v[54:57], v[168:171], v[176:179], v[54:57]
	s_barrier
	s_add_i32 s57, 0, 0x18000
	s_add_i32 s58, 0, 0x1c000
	v_add_u32_e32 v156, s57, v145
	v_add_u32_e32 v172, s58, v145
	ds_read_b128 v[140:143], v156
	ds_read_b128 v[148:151], v156 offset:1024
	ds_read_b128 v[152:155], v156 offset:2048
	ds_read_b128 v[156:159], v156 offset:3072
	ds_read_b128 v[160:163], v172
	ds_read_b128 v[164:167], v172 offset:1024
	ds_read_b128 v[168:171], v172 offset:2048
	ds_read_b128 v[172:175], v172 offset:3072
	s_add_u32 s38, s38, 0x40000
	s_addc_u32 s39, s39, 0
	s_mov_b32 m0, s45
	v_lshl_add_u64 v[216:217], s[38:39], 0, v[130:131]
	ds_read_b128 v[176:179], v147 offset:32768
	ds_read_b128 v[180:183], v147 offset:33792
	ds_read_b128 v[184:187], v147 offset:34816
	ds_read_b128 v[188:191], v147 offset:35840
	ds_read_b128 v[192:195], v147 offset:36864
	ds_read_b128 v[196:199], v147 offset:37888
	ds_read_b128 v[200:203], v147 offset:38912
	ds_read_b128 v[204:207], v147 offset:39936
	global_load_lds_dwordx4 v[216:217], off
	v_lshl_add_u64 v[216:217], s[38:39], 0, v[132:133]
	s_mov_b32 m0, s47
	s_nop 0
	global_load_lds_dwordx4 v[216:217], off
	s_waitcnt vmcnt(8)
	s_waitcnt lgkmcnt(0)
	s_barrier
	s_waitcnt lgkmcnt(0)
	v_mfma_f32_16x16x32_bf16 v[122:125], v[140:143], v[176:179], v[122:125]
	v_mfma_f32_16x16x32_bf16 v[122:125], v[148:151], v[180:183], v[122:125]
	v_mfma_f32_16x16x32_bf16 v[106:109], v[148:151], v[188:191], v[106:109]
	v_mfma_f32_16x16x32_bf16 v[106:109], v[140:143], v[184:187], v[106:109]
	v_mfma_f32_16x16x32_bf16 v[90:93], v[140:143], v[192:195], v[90:93]
	v_mfma_f32_16x16x32_bf16 v[90:93], v[148:151], v[196:199], v[90:93]
	v_mfma_f32_16x16x32_bf16 v[74:77], v[148:151], v[204:207], v[74:77]
	v_mfma_f32_16x16x32_bf16 v[74:77], v[140:143], v[200:203], v[74:77]
	v_mfma_f32_16x16x32_bf16 v[66:69], v[152:155], v[200:203], v[66:69]
	v_mfma_f32_16x16x32_bf16 v[66:69], v[156:159], v[204:207], v[66:69]
	v_mfma_f32_16x16x32_bf16 v[82:85], v[156:159], v[196:199], v[82:85]
	v_mfma_f32_16x16x32_bf16 v[82:85], v[152:155], v[192:195], v[82:85]
	v_mfma_f32_16x16x32_bf16 v[98:101], v[152:155], v[184:187], v[98:101]
	v_mfma_f32_16x16x32_bf16 v[98:101], v[156:159], v[188:191], v[98:101]
	v_mfma_f32_16x16x32_bf16 v[114:117], v[156:159], v[180:183], v[114:117]
	v_mfma_f32_16x16x32_bf16 v[114:117], v[152:155], v[176:179], v[114:117]
	v_mfma_f32_16x16x32_bf16 v[126:129], v[160:163], v[176:179], v[126:129]
	v_mfma_f32_16x16x32_bf16 v[126:129], v[164:167], v[180:183], v[126:129]
	v_mfma_f32_16x16x32_bf16 v[110:113], v[164:167], v[188:191], v[110:113]
	v_mfma_f32_16x16x32_bf16 v[110:113], v[160:163], v[184:187], v[110:113]
	v_mfma_f32_16x16x32_bf16 v[94:97], v[160:163], v[192:195], v[94:97]
	v_mfma_f32_16x16x32_bf16 v[94:97], v[164:167], v[196:199], v[94:97]
	v_mfma_f32_16x16x32_bf16 v[78:81], v[164:167], v[204:207], v[78:81]
	v_mfma_f32_16x16x32_bf16 v[78:81], v[160:163], v[200:203], v[78:81]
	v_mfma_f32_16x16x32_bf16 v[70:73], v[168:171], v[200:203], v[70:73]
	v_mfma_f32_16x16x32_bf16 v[70:73], v[172:175], v[204:207], v[70:73]
	v_mfma_f32_16x16x32_bf16 v[86:89], v[172:175], v[196:199], v[86:89]
	v_mfma_f32_16x16x32_bf16 v[86:89], v[168:171], v[192:195], v[86:89]
	v_mfma_f32_16x16x32_bf16 v[102:105], v[168:171], v[184:187], v[102:105]
	v_mfma_f32_16x16x32_bf16 v[102:105], v[172:175], v[188:191], v[102:105]
	v_mfma_f32_16x16x32_bf16 v[118:121], v[172:175], v[180:183], v[118:121]
	v_mfma_f32_16x16x32_bf16 v[118:121], v[168:171], v[176:179], v[118:121]
	s_barrier
	s_add_i32 s38, s57, s43
	v_lshl_add_u64 v[208:209], v[208:209], 0, s[98:99]
	s_mov_b32 m0, s38
	ds_read_b128 v[176:179], v147 offset:49152
	ds_read_b128 v[180:183], v147 offset:50176
	ds_read_b128 v[184:187], v147 offset:51200
	ds_read_b128 v[188:191], v147 offset:52224
	ds_read_b128 v[192:195], v147 offset:53248
	ds_read_b128 v[196:199], v147 offset:54272
	ds_read_b128 v[200:203], v147 offset:55296
	ds_read_b128 v[204:207], v147 offset:56320
	global_load_lds_dwordx4 v[208:209], off
	s_add_i32 m0, s38, 0x2000
	s_add_u32 s30, s30, 0x40080
	v_lshl_add_u64 v[208:209], v[210:211], 0, s[98:99]
	s_addc_u32 s31, s31, 0
	s_add_i32 s38, s58, s43
	global_load_lds_dwordx4 v[208:209], off
	v_lshl_add_u64 v[208:209], s[30:31], 0, v[0:1]
	s_mov_b32 m0, s38
	s_nop 0
	global_load_lds_dwordx4 v[208:209], off
	v_lshl_add_u64 v[208:209], s[30:31], 0, v[134:135]
	s_add_i32 m0, s38, 0x2000
	s_nop 0
	global_load_lds_dwordx4 v[208:209], off
	v_lshl_add_u64 v[208:209], v[212:213], 0, s[98:99]
	s_mov_b32 m0, s49
	s_nop 0
	global_load_lds_dwordx4 v[208:209], off
	v_lshl_add_u64 v[208:209], v[214:215], 0, s[98:99]
	s_mov_b32 m0, s51
	s_nop 0
	global_load_lds_dwordx4 v[208:209], off
	s_waitcnt vmcnt(8)
	s_waitcnt lgkmcnt(0)
	s_barrier
	s_waitcnt lgkmcnt(0)
	v_mfma_f32_16x16x32_bf16 v[58:61], v[140:143], v[176:179], v[58:61]
	v_mfma_f32_16x16x32_bf16 v[58:61], v[148:151], v[180:183], v[58:61]
	v_mfma_f32_16x16x32_bf16 v[42:45], v[148:151], v[188:191], v[42:45]
	v_mfma_f32_16x16x32_bf16 v[42:45], v[140:143], v[184:187], v[42:45]
	v_mfma_f32_16x16x32_bf16 v[26:29], v[140:143], v[192:195], v[26:29]
	v_mfma_f32_16x16x32_bf16 v[26:29], v[148:151], v[196:199], v[26:29]
	v_mfma_f32_16x16x32_bf16 v[10:13], v[148:151], v[204:207], v[10:13]
	v_mfma_f32_16x16x32_bf16 v[10:13], v[140:143], v[200:203], v[10:13]
	v_mfma_f32_16x16x32_bf16 v[6:9], v[152:155], v[200:203], v[6:9]
	v_mfma_f32_16x16x32_bf16 v[6:9], v[156:159], v[204:207], v[6:9]
	v_mfma_f32_16x16x32_bf16 v[18:21], v[156:159], v[196:199], v[18:21]
	v_mfma_f32_16x16x32_bf16 v[18:21], v[152:155], v[192:195], v[18:21]
	v_mfma_f32_16x16x32_bf16 v[34:37], v[152:155], v[184:187], v[34:37]
	v_mfma_f32_16x16x32_bf16 v[34:37], v[156:159], v[188:191], v[34:37]
	v_mfma_f32_16x16x32_bf16 v[50:53], v[156:159], v[180:183], v[50:53]
	v_mfma_f32_16x16x32_bf16 v[50:53], v[152:155], v[176:179], v[50:53]
	v_mfma_f32_16x16x32_bf16 v[62:65], v[160:163], v[176:179], v[62:65]
	v_mfma_f32_16x16x32_bf16 v[62:65], v[164:167], v[180:183], v[62:65]
	v_mfma_f32_16x16x32_bf16 v[46:49], v[164:167], v[188:191], v[46:49]
	v_mfma_f32_16x16x32_bf16 v[46:49], v[160:163], v[184:187], v[46:49]
	v_mfma_f32_16x16x32_bf16 v[30:33], v[160:163], v[192:195], v[30:33]
	v_mfma_f32_16x16x32_bf16 v[30:33], v[164:167], v[196:199], v[30:33]
	v_mfma_f32_16x16x32_bf16 v[14:17], v[164:167], v[204:207], v[14:17]
	v_mfma_f32_16x16x32_bf16 v[14:17], v[160:163], v[200:203], v[14:17]
	v_mfma_f32_16x16x32_bf16 v[2:5], v[168:171], v[200:203], v[2:5]
	v_mfma_f32_16x16x32_bf16 v[2:5], v[172:175], v[204:207], v[2:5]
	v_mfma_f32_16x16x32_bf16 v[22:25], v[172:175], v[196:199], v[22:25]
	v_mfma_f32_16x16x32_bf16 v[22:25], v[168:171], v[192:195], v[22:25]
	v_mfma_f32_16x16x32_bf16 v[38:41], v[168:171], v[184:187], v[38:41]
	v_mfma_f32_16x16x32_bf16 v[38:41], v[172:175], v[188:191], v[38:41]
	v_mfma_f32_16x16x32_bf16 v[54:57], v[172:175], v[180:183], v[54:57]
	v_mfma_f32_16x16x32_bf16 v[54:57], v[168:171], v[176:179], v[54:57]
	s_barrier
	s_add_i32 s56, s56, 2
	s_add_u32 s28, s28, 0x100
	s_addc_u32 s29, s29, 0
	s_add_u32 s54, s54, 0x100
	s_addc_u32 s55, s55, 0
	s_cmp_gt_u32 s56, 13
	s_cbranch_scc1 .Lpeel_done_374
.LBB0_374:
	s_add_u32 s30, s28, 0xfffc0080
	s_addc_u32 s31, s29, -1
	s_add_i32 s57, 0, 0x10000
	s_cmp_eq_u32 s56, 12
	s_cselect_b32 s39, s17, s31
	s_cselect_b32 s38, s25, s30
	s_cselect_b32 s31, s15, s55
	s_cselect_b32 s30, s53, s54
	s_add_i32 s60, 0, 0x14000
	v_add_u32_e32 v156, s57, v145
	v_add_u32_e32 v172, s60, v145
	ds_read_b128 v[140:143], v156
	ds_read_b128 v[148:151], v156 offset:1024
	ds_read_b128 v[152:155], v156 offset:2048
	ds_read_b128 v[156:159], v156 offset:3072
	ds_read_b128 v[160:163], v172
	ds_read_b128 v[164:167], v172 offset:1024
	ds_read_b128 v[168:171], v172 offset:2048
	ds_read_b128 v[172:175], v172 offset:3072
	v_lshl_add_u64 v[208:209], s[28:29], 0, v[136:137]
	s_add_i32 m0, s27, 0xc000
	ds_read_b128 v[176:179], v147
	ds_read_b128 v[180:183], v147 offset:1024
	ds_read_b128 v[184:187], v147 offset:2048
	ds_read_b128 v[188:191], v147 offset:3072
	ds_read_b128 v[192:195], v147 offset:4096
	ds_read_b128 v[196:199], v147 offset:5120
	ds_read_b128 v[200:203], v147 offset:6144
	ds_read_b128 v[204:207], v147 offset:7168
	global_load_lds_dwordx4 v[208:209], off
	v_lshl_add_u64 v[208:209], s[28:29], 0, v[138:139]
	s_add_i32 m0, s27, 0xe000
	s_nop 0
	global_load_lds_dwordx4 v[208:209], off
	s_waitcnt vmcnt(8)
	s_waitcnt lgkmcnt(0)
	s_barrier
	s_waitcnt lgkmcnt(0)
	v_mfma_f32_16x16x32_bf16 v[122:125], v[140:143], v[176:179], v[122:125]
	v_mfma_f32_16x16x32_bf16 v[122:125], v[148:151], v[180:183], v[122:125]
	v_mfma_f32_16x16x32_bf16 v[106:109], v[148:151], v[188:191], v[106:109]
	v_mfma_f32_16x16x32_bf16 v[106:109], v[140:143], v[184:187], v[106:109]
	v_mfma_f32_16x16x32_bf16 v[90:93], v[140:143], v[192:195], v[90:93]
	v_mfma_f32_16x16x32_bf16 v[90:93], v[148:151], v[196:199], v[90:93]
	v_mfma_f32_16x16x32_bf16 v[74:77], v[148:151], v[204:207], v[74:77]
	v_mfma_f32_16x16x32_bf16 v[74:77], v[140:143], v[200:203], v[74:77]
	v_mfma_f32_16x16x32_bf16 v[66:69], v[152:155], v[200:203], v[66:69]
	v_mfma_f32_16x16x32_bf16 v[66:69], v[156:159], v[204:207], v[66:69]
	v_mfma_f32_16x16x32_bf16 v[82:85], v[156:159], v[196:199], v[82:85]
	v_mfma_f32_16x16x32_bf16 v[82:85], v[152:155], v[192:195], v[82:85]
	v_mfma_f32_16x16x32_bf16 v[98:101], v[152:155], v[184:187], v[98:101]
	v_mfma_f32_16x16x32_bf16 v[98:101], v[156:159], v[188:191], v[98:101]
	v_mfma_f32_16x16x32_bf16 v[114:117], v[156:159], v[180:183], v[114:117]
	v_mfma_f32_16x16x32_bf16 v[114:117], v[152:155], v[176:179], v[114:117]
	v_mfma_f32_16x16x32_bf16 v[126:129], v[160:163], v[176:179], v[126:129]
	v_mfma_f32_16x16x32_bf16 v[126:129], v[164:167], v[180:183], v[126:129]
	v_mfma_f32_16x16x32_bf16 v[110:113], v[164:167], v[188:191], v[110:113]
	v_mfma_f32_16x16x32_bf16 v[110:113], v[160:163], v[184:187], v[110:113]
	v_mfma_f32_16x16x32_bf16 v[94:97], v[160:163], v[192:195], v[94:97]
	v_mfma_f32_16x16x32_bf16 v[94:97], v[164:167], v[196:199], v[94:97]
	v_mfma_f32_16x16x32_bf16 v[78:81], v[164:167], v[204:207], v[78:81]
	v_mfma_f32_16x16x32_bf16 v[78:81], v[160:163], v[200:203], v[78:81]
	v_mfma_f32_16x16x32_bf16 v[70:73], v[168:171], v[200:203], v[70:73]
	v_mfma_f32_16x16x32_bf16 v[70:73], v[172:175], v[204:207], v[70:73]
	v_mfma_f32_16x16x32_bf16 v[86:89], v[172:175], v[196:199], v[86:89]
	v_mfma_f32_16x16x32_bf16 v[86:89], v[168:171], v[192:195], v[86:89]
	v_mfma_f32_16x16x32_bf16 v[102:105], v[168:171], v[184:187], v[102:105]
	v_mfma_f32_16x16x32_bf16 v[102:105], v[172:175], v[188:191], v[102:105]
	v_mfma_f32_16x16x32_bf16 v[118:121], v[172:175], v[180:183], v[118:121]
	v_mfma_f32_16x16x32_bf16 v[118:121], v[168:171], v[176:179], v[118:121]
	s_barrier
	s_add_i32 s57, s57, s43
	v_lshl_add_u64 v[208:209], s[30:31], 0, v[0:1]
	s_mov_b32 m0, s57
	ds_read_b128 v[176:179], v147 offset:16384
	ds_read_b128 v[180:183], v147 offset:17408
	ds_read_b128 v[184:187], v147 offset:18432
	ds_read_b128 v[188:191], v147 offset:19456
	ds_read_b128 v[192:195], v147 offset:20480
	ds_read_b128 v[196:199], v147 offset:21504
	ds_read_b128 v[200:203], v147 offset:22528
	ds_read_b128 v[204:207], v147 offset:23552
	global_load_lds_dwordx4 v[208:209], off
	s_add_i32 m0, s57, 0x2000
	s_add_u32 s58, s30, 0x40000
	v_lshl_add_u64 v[210:211], s[30:31], 0, v[134:135]
	s_addc_u32 s59, s31, 0
	s_add_i32 s57, s60, s43
	global_load_lds_dwordx4 v[210:211], off
	v_lshl_add_u64 v[212:213], s[58:59], 0, v[0:1]
	s_mov_b32 m0, s57
	v_lshl_add_u64 v[214:215], s[38:39], 0, v[132:133]
	global_load_lds_dwordx4 v[212:213], off
	v_lshl_add_u64 v[212:213], s[58:59], 0, v[134:135]
	s_add_i32 m0, s57, 0x2000
	s_nop 0
	global_load_lds_dwordx4 v[212:213], off
	v_lshl_add_u64 v[212:213], s[38:39], 0, v[130:131]
	s_mov_b32 m0, s27
	s_nop 0
	global_load_lds_dwordx4 v[212:213], off
	s_mov_b32 m0, s44
	s_nop 0
	global_load_lds_dwordx4 v[214:215], off
	s_waitcnt vmcnt(8)
	s_waitcnt lgkmcnt(0)
	s_barrier
	s_waitcnt lgkmcnt(0)
	v_mfma_f32_16x16x32_bf16 v[58:61], v[140:143], v[176:179], v[58:61]
	v_mfma_f32_16x16x32_bf16 v[58:61], v[148:151], v[180:183], v[58:61]
	v_mfma_f32_16x16x32_bf16 v[42:45], v[148:151], v[188:191], v[42:45]
	v_mfma_f32_16x16x32_bf16 v[42:45], v[140:143], v[184:187], v[42:45]
	v_mfma_f32_16x16x32_bf16 v[26:29], v[140:143], v[192:195], v[26:29]
	v_mfma_f32_16x16x32_bf16 v[26:29], v[148:151], v[196:199], v[26:29]
	v_mfma_f32_16x16x32_bf16 v[10:13], v[148:151], v[204:207], v[10:13]
	v_mfma_f32_16x16x32_bf16 v[10:13], v[140:143], v[200:203], v[10:13]
	v_mfma_f32_16x16x32_bf16 v[6:9], v[152:155], v[200:203], v[6:9]
	v_mfma_f32_16x16x32_bf16 v[6:9], v[156:159], v[204:207], v[6:9]
	v_mfma_f32_16x16x32_bf16 v[18:21], v[156:159], v[196:199], v[18:21]
	v_mfma_f32_16x16x32_bf16 v[18:21], v[152:155], v[192:195], v[18:21]
	v_mfma_f32_16x16x32_bf16 v[34:37], v[152:155], v[184:187], v[34:37]
	v_mfma_f32_16x16x32_bf16 v[34:37], v[156:159], v[188:191], v[34:37]
	v_mfma_f32_16x16x32_bf16 v[50:53], v[156:159], v[180:183], v[50:53]
	v_mfma_f32_16x16x32_bf16 v[50:53], v[152:155], v[176:179], v[50:53]
	v_mfma_f32_16x16x32_bf16 v[62:65], v[160:163], v[176:179], v[62:65]
	v_mfma_f32_16x16x32_bf16 v[62:65], v[164:167], v[180:183], v[62:65]
	v_mfma_f32_16x16x32_bf16 v[46:49], v[164:167], v[188:191], v[46:49]
	v_mfma_f32_16x16x32_bf16 v[46:49], v[160:163], v[184:187], v[46:49]
	v_mfma_f32_16x16x32_bf16 v[30:33], v[160:163], v[192:195], v[30:33]
	v_mfma_f32_16x16x32_bf16 v[30:33], v[164:167], v[196:199], v[30:33]
	v_mfma_f32_16x16x32_bf16 v[14:17], v[164:167], v[204:207], v[14:17]
	v_mfma_f32_16x16x32_bf16 v[14:17], v[160:163], v[200:203], v[14:17]
	v_mfma_f32_16x16x32_bf16 v[2:5], v[168:171], v[200:203], v[2:5]
	v_mfma_f32_16x16x32_bf16 v[2:5], v[172:175], v[204:207], v[2:5]
	v_mfma_f32_16x16x32_bf16 v[22:25], v[172:175], v[196:199], v[22:25]
	v_mfma_f32_16x16x32_bf16 v[22:25], v[168:171], v[192:195], v[22:25]
	v_mfma_f32_16x16x32_bf16 v[38:41], v[168:171], v[184:187], v[38:41]
	v_mfma_f32_16x16x32_bf16 v[38:41], v[172:175], v[188:191], v[38:41]
	v_mfma_f32_16x16x32_bf16 v[54:57], v[172:175], v[180:183], v[54:57]
	v_mfma_f32_16x16x32_bf16 v[54:57], v[168:171], v[176:179], v[54:57]
	s_barrier
	s_add_i32 s57, 0, 0x18000
	s_add_i32 s58, 0, 0x1c000
	v_add_u32_e32 v156, s57, v145
	v_add_u32_e32 v172, s58, v145
	ds_read_b128 v[140:143], v156
	ds_read_b128 v[148:151], v156 offset:1024
	ds_read_b128 v[152:155], v156 offset:2048
	ds_read_b128 v[156:159], v156 offset:3072
	ds_read_b128 v[160:163], v172
	ds_read_b128 v[164:167], v172 offset:1024
	ds_read_b128 v[168:171], v172 offset:2048
	ds_read_b128 v[172:175], v172 offset:3072
	s_add_u32 s38, s38, 0x40000
	s_addc_u32 s39, s39, 0
	s_mov_b32 m0, s45
	v_lshl_add_u64 v[216:217], s[38:39], 0, v[130:131]
	ds_read_b128 v[176:179], v147 offset:32768
	ds_read_b128 v[180:183], v147 offset:33792
	ds_read_b128 v[184:187], v147 offset:34816
	ds_read_b128 v[188:191], v147 offset:35840
	ds_read_b128 v[192:195], v147 offset:36864
	ds_read_b128 v[196:199], v147 offset:37888
	ds_read_b128 v[200:203], v147 offset:38912
	ds_read_b128 v[204:207], v147 offset:39936
	global_load_lds_dwordx4 v[216:217], off
	v_lshl_add_u64 v[216:217], s[38:39], 0, v[132:133]
	s_mov_b32 m0, s47
	s_nop 0
	global_load_lds_dwordx4 v[216:217], off
	s_waitcnt vmcnt(8)
	s_waitcnt lgkmcnt(0)
	s_barrier
	s_waitcnt lgkmcnt(0)
	v_mfma_f32_16x16x32_bf16 v[122:125], v[140:143], v[176:179], v[122:125]
	v_mfma_f32_16x16x32_bf16 v[122:125], v[148:151], v[180:183], v[122:125]
	v_mfma_f32_16x16x32_bf16 v[106:109], v[148:151], v[188:191], v[106:109]
	v_mfma_f32_16x16x32_bf16 v[106:109], v[140:143], v[184:187], v[106:109]
	v_mfma_f32_16x16x32_bf16 v[90:93], v[140:143], v[192:195], v[90:93]
	v_mfma_f32_16x16x32_bf16 v[90:93], v[148:151], v[196:199], v[90:93]
	v_mfma_f32_16x16x32_bf16 v[74:77], v[148:151], v[204:207], v[74:77]
	v_mfma_f32_16x16x32_bf16 v[74:77], v[140:143], v[200:203], v[74:77]
	v_mfma_f32_16x16x32_bf16 v[66:69], v[152:155], v[200:203], v[66:69]
	v_mfma_f32_16x16x32_bf16 v[66:69], v[156:159], v[204:207], v[66:69]
	v_mfma_f32_16x16x32_bf16 v[82:85], v[156:159], v[196:199], v[82:85]
	v_mfma_f32_16x16x32_bf16 v[82:85], v[152:155], v[192:195], v[82:85]
	v_mfma_f32_16x16x32_bf16 v[98:101], v[152:155], v[184:187], v[98:101]
	v_mfma_f32_16x16x32_bf16 v[98:101], v[156:159], v[188:191], v[98:101]
	v_mfma_f32_16x16x32_bf16 v[114:117], v[156:159], v[180:183], v[114:117]
	v_mfma_f32_16x16x32_bf16 v[114:117], v[152:155], v[176:179], v[114:117]
	v_mfma_f32_16x16x32_bf16 v[126:129], v[160:163], v[176:179], v[126:129]
	v_mfma_f32_16x16x32_bf16 v[126:129], v[164:167], v[180:183], v[126:129]
	v_mfma_f32_16x16x32_bf16 v[110:113], v[164:167], v[188:191], v[110:113]
	v_mfma_f32_16x16x32_bf16 v[110:113], v[160:163], v[184:187], v[110:113]
	v_mfma_f32_16x16x32_bf16 v[94:97], v[160:163], v[192:195], v[94:97]
	v_mfma_f32_16x16x32_bf16 v[94:97], v[164:167], v[196:199], v[94:97]
	v_mfma_f32_16x16x32_bf16 v[78:81], v[164:167], v[204:207], v[78:81]
	v_mfma_f32_16x16x32_bf16 v[78:81], v[160:163], v[200:203], v[78:81]
	v_mfma_f32_16x16x32_bf16 v[70:73], v[168:171], v[200:203], v[70:73]
	v_mfma_f32_16x16x32_bf16 v[70:73], v[172:175], v[204:207], v[70:73]
	v_mfma_f32_16x16x32_bf16 v[86:89], v[172:175], v[196:199], v[86:89]
	v_mfma_f32_16x16x32_bf16 v[86:89], v[168:171], v[192:195], v[86:89]
	v_mfma_f32_16x16x32_bf16 v[102:105], v[168:171], v[184:187], v[102:105]
	v_mfma_f32_16x16x32_bf16 v[102:105], v[172:175], v[188:191], v[102:105]
	v_mfma_f32_16x16x32_bf16 v[118:121], v[172:175], v[180:183], v[118:121]
	v_mfma_f32_16x16x32_bf16 v[118:121], v[168:171], v[176:179], v[118:121]
	s_barrier
	s_add_i32 s38, s57, s43
	v_lshl_add_u64 v[208:209], v[208:209], 0, s[98:99]
	s_mov_b32 m0, s38
	ds_read_b128 v[176:179], v147 offset:49152
	ds_read_b128 v[180:183], v147 offset:50176
	ds_read_b128 v[184:187], v147 offset:51200
	ds_read_b128 v[188:191], v147 offset:52224
	ds_read_b128 v[192:195], v147 offset:53248
	ds_read_b128 v[196:199], v147 offset:54272
	ds_read_b128 v[200:203], v147 offset:55296
	ds_read_b128 v[204:207], v147 offset:56320
	global_load_lds_dwordx4 v[208:209], off
	s_add_i32 m0, s38, 0x2000
	s_add_u32 s30, s30, 0x40080
	v_lshl_add_u64 v[208:209], v[210:211], 0, s[98:99]
	s_addc_u32 s31, s31, 0
	s_add_i32 s38, s58, s43
	global_load_lds_dwordx4 v[208:209], off
	v_lshl_add_u64 v[208:209], s[30:31], 0, v[0:1]
	s_mov_b32 m0, s38
	s_nop 0
	global_load_lds_dwordx4 v[208:209], off
	v_lshl_add_u64 v[208:209], s[30:31], 0, v[134:135]
	s_add_i32 m0, s38, 0x2000
	s_nop 0
	global_load_lds_dwordx4 v[208:209], off
	v_lshl_add_u64 v[208:209], v[212:213], 0, s[98:99]
	s_mov_b32 m0, s49
	s_nop 0
	global_load_lds_dwordx4 v[208:209], off
	v_lshl_add_u64 v[208:209], v[214:215], 0, s[98:99]
	s_mov_b32 m0, s51
	s_nop 0
	global_load_lds_dwordx4 v[208:209], off
	s_waitcnt vmcnt(8)
	s_waitcnt lgkmcnt(0)
	s_barrier
	s_waitcnt lgkmcnt(0)
	v_mfma_f32_16x16x32_bf16 v[58:61], v[140:143], v[176:179], v[58:61]
	v_mfma_f32_16x16x32_bf16 v[58:61], v[148:151], v[180:183], v[58:61]
	v_mfma_f32_16x16x32_bf16 v[42:45], v[148:151], v[188:191], v[42:45]
	v_mfma_f32_16x16x32_bf16 v[42:45], v[140:143], v[184:187], v[42:45]
	v_mfma_f32_16x16x32_bf16 v[26:29], v[140:143], v[192:195], v[26:29]
	v_mfma_f32_16x16x32_bf16 v[26:29], v[148:151], v[196:199], v[26:29]
	v_mfma_f32_16x16x32_bf16 v[10:13], v[148:151], v[204:207], v[10:13]
	v_mfma_f32_16x16x32_bf16 v[10:13], v[140:143], v[200:203], v[10:13]
	v_mfma_f32_16x16x32_bf16 v[6:9], v[152:155], v[200:203], v[6:9]
	v_mfma_f32_16x16x32_bf16 v[6:9], v[156:159], v[204:207], v[6:9]
	v_mfma_f32_16x16x32_bf16 v[18:21], v[156:159], v[196:199], v[18:21]
	v_mfma_f32_16x16x32_bf16 v[18:21], v[152:155], v[192:195], v[18:21]
	v_mfma_f32_16x16x32_bf16 v[34:37], v[152:155], v[184:187], v[34:37]
	v_mfma_f32_16x16x32_bf16 v[34:37], v[156:159], v[188:191], v[34:37]
	v_mfma_f32_16x16x32_bf16 v[50:53], v[156:159], v[180:183], v[50:53]
	v_mfma_f32_16x16x32_bf16 v[50:53], v[152:155], v[176:179], v[50:53]
	v_mfma_f32_16x16x32_bf16 v[62:65], v[160:163], v[176:179], v[62:65]
	v_mfma_f32_16x16x32_bf16 v[62:65], v[164:167], v[180:183], v[62:65]
	v_mfma_f32_16x16x32_bf16 v[46:49], v[164:167], v[188:191], v[46:49]
	v_mfma_f32_16x16x32_bf16 v[46:49], v[160:163], v[184:187], v[46:49]
	v_mfma_f32_16x16x32_bf16 v[30:33], v[160:163], v[192:195], v[30:33]
	v_mfma_f32_16x16x32_bf16 v[30:33], v[164:167], v[196:199], v[30:33]
	v_mfma_f32_16x16x32_bf16 v[14:17], v[164:167], v[204:207], v[14:17]
	v_mfma_f32_16x16x32_bf16 v[14:17], v[160:163], v[200:203], v[14:17]
	v_mfma_f32_16x16x32_bf16 v[2:5], v[168:171], v[200:203], v[2:5]
	v_mfma_f32_16x16x32_bf16 v[2:5], v[172:175], v[204:207], v[2:5]
	v_mfma_f32_16x16x32_bf16 v[22:25], v[172:175], v[196:199], v[22:25]
	v_mfma_f32_16x16x32_bf16 v[22:25], v[168:171], v[192:195], v[22:25]
	v_mfma_f32_16x16x32_bf16 v[38:41], v[168:171], v[184:187], v[38:41]
	v_mfma_f32_16x16x32_bf16 v[38:41], v[172:175], v[188:191], v[38:41]
	v_mfma_f32_16x16x32_bf16 v[54:57], v[172:175], v[180:183], v[54:57]
	v_mfma_f32_16x16x32_bf16 v[54:57], v[168:171], v[176:179], v[54:57]
	s_barrier
	s_add_i32 s56, s56, 2
	s_add_u32 s28, s28, 0x100
	s_addc_u32 s29, s29, 0
	s_add_u32 s54, s54, 0x100
	s_addc_u32 s55, s55, 0
	s_cmp_gt_u32 s56, 13
	s_cbranch_scc0 .LBB0_374
